# speedup vs baseline: 1.0036x; 1.0004x over previous
; __device__ __forceinline__ float gelu_f(float x) {
;   const float c2 = 2.f * 0.7978845608028654f * 1.4426950408889634f;
;   float p = __builtin_fmaf(x * x, 0.044715f * c2, c2);
;   float e = __builtin_amdgcn_exp2f(-x * p);
;   return x * __builtin_amdgcn_rcpf(1.f + e);
; }
; template <int MODE>
; __device__ __forceinline__ void gemm_tile(const int ph, const int which, const int pm, const int pn) {
;     ...
;   for (int ai = 0; ai < 2; ++ai)
;     for (int m = 0; m < 4; ++m) {
;       const int row = browC + ai * HALF + wr * 64 + m * 16 + fr;
;       float s = 1.f;
;       if (MODE == 1) s = scale[row];
;       for (int bj = 0; bj < 2; ++bj) {
;         uint2 o[2];
; #pragma unroll
;         for (int n = 0; n < 2; ++n) {
;           const int col = ecol + bj * HALF + wc * 32 + n * 16 + fq * 4;
;           f32x4 v = acc[ai][bj][m][n];
;           float x0, x1, x2, x3;
;           if (MODE == 2) {
;             float4 c4 = *(const float4*)(scale + col);
;             x0 = v[0] * c4.x; x1 = v[1] * c4.y; x2 = v[2] * c4.z; x3 = v[3] * c4.w;
;           } else {
;             x0 = v[0] * s; x1 = v[1] * s; x2 = v[2] * s; x3 = v[3] * s;
;           }
;           if (MODE == 1 && act) { x0 = gelu_f(x0); x1 = gelu_f(x1); x2 = gelu_f(x2); x3 = gelu_f(x3); }
;           o[n].x = pack2(x0, x1);
;           o[n].y = pack2(x2, x3);
;         }
;         auto rx = __builtin_amdgcn_permlane16_swap(o[0].x, o[1].x, false, false);
;         auto ry = __builtin_amdgcn_permlane16_swap(o[0].y, o[1].y, false, false);
;         const int colw = ecol + bj * HALF + wc * 32 + (fq & 1) * 16 + (fq >> 1) * 8;
;         *(uint4*)(C + (size_t)row * ldc + colw) = make_uint4(rx[0], ry[0], rx[1], ry[1]);
;       }
;     }
.LBB0_266:
	v_mov_b32_e32 v184, 0x3dd2d3e7
	v_mov_b32_e32 v185, 0x3dd2d3e7
	v_mov_b32_e32 v186, v209
	v_mov_b32_e32 v187, v209
	v_mov_b32_e32 v188, 1.0
	v_mov_b32_e32 v189, 1.0
	v_add_u32_e32 v130, s26, v130
	v_ashrrev_i32_e32 v131, 31, v130
	v_lshl_add_u64 v[132:133], v[130:131], 2, s[16:17]
	global_load_dword v176, v[132:133], off
	global_load_dword v177, v[132:133], off offset:64
	global_load_dword v178, v[132:133], off offset:128
	global_load_dword v179, v[132:133], off offset:192
	global_load_dword v180, v[132:133], off offset:512
	global_load_dword v181, v[132:133], off offset:576
	global_load_dword v182, v[132:133], off offset:640
	global_load_dword v183, v[132:133], off offset:704
	s_and_b64 vcc, exec, s[10:11]
	s_waitcnt vmcnt(0)
	v_mov_b32_e32 v134, v176
	v_pk_mul_f32 v[126:127], v[126:127], v[134:135] op_sel_hi:[1,0]
	v_pk_mul_f32 v[128:129], v[128:129], v[134:135] op_sel_hi:[1,0]
	s_cbranch_vccnz .LBB0_268
	v_pk_mul_f32 v[136:137], v[126:127], v[126:127]
	s_nop 0
	s_nop 0
	s_nop 0
	v_pk_fma_f32 v[136:137], v[136:137], v[184:185], v[186:187]
	s_nop 0
	v_pk_mul_f32 v[136:137], v[136:137], v[126:127] neg_lo:[0,1] neg_hi:[0,1]
	s_nop 0
	v_exp_f32_e32 v136, v136
	v_exp_f32_e32 v137, v137
	s_nop 0
	v_pk_add_f32 v[136:137], v[136:137], v[188:189]
	s_nop 0
	v_rcp_f32_e32 v136, v136
	v_rcp_f32_e32 v137, v137
	s_nop 0
	s_nop 0
	v_pk_mul_f32 v[126:127], v[126:127], v[136:137]
	v_pk_mul_f32 v[136:137], v[128:129], v[128:129]
	s_nop 0
	s_nop 0
	s_nop 0
	v_pk_fma_f32 v[136:137], v[136:137], v[184:185], v[186:187]
	s_nop 0
	v_pk_mul_f32 v[136:137], v[136:137], v[128:129] neg_lo:[0,1] neg_hi:[0,1]
	s_nop 0
	v_exp_f32_e32 v136, v136
	v_exp_f32_e32 v137, v137
	s_nop 0
	v_pk_add_f32 v[136:137], v[136:137], v[188:189]
	s_nop 0
	v_rcp_f32_e32 v136, v136
	v_rcp_f32_e32 v137, v137
	s_nop 0
	s_nop 0
	v_pk_mul_f32 v[128:129], v[128:129], v[136:137]
.LBB0_268:
	v_mov_b32_e32 v135, v134
	s_xor_b64 s[10:11], s[10:11], -1
	v_pk_mul_f32 v[136:137], v[122:123], v[134:135]
	v_cndmask_b32_e64 v122, 0, 1, s[10:11]
	v_cmp_ne_u32_e64 s[4:5], 1, v122
	s_andn2_b64 vcc, exec, s[10:11]
	v_pk_mul_f32 v[124:125], v[124:125], v[134:135]
	s_cbranch_vccnz .LBB0_270
	v_pk_mul_f32 v[122:123], v[136:137], v[136:137]
	s_nop 0
	v_pk_fma_f32 v[122:123], v[122:123], v[184:185], v[186:187]
	s_nop 0
	v_pk_mul_f32 v[122:123], v[122:123], v[136:137] neg_lo:[0,1] neg_hi:[0,1]
	s_nop 0
	v_exp_f32_e32 v122, v122
	v_exp_f32_e32 v123, v123
	s_nop 0
	v_pk_add_f32 v[122:123], v[122:123], v[188:189]
	s_nop 0
	v_rcp_f32_e32 v122, v122
	v_rcp_f32_e32 v123, v123
	s_nop 0
	s_nop 0
	v_pk_mul_f32 v[136:137], v[136:137], v[122:123]
	v_pk_mul_f32 v[122:123], v[124:125], v[124:125]
	s_nop 0
	v_pk_fma_f32 v[122:123], v[122:123], v[184:185], v[186:187]
	s_nop 0
	v_pk_mul_f32 v[122:123], v[122:123], v[124:125] neg_lo:[0,1] neg_hi:[0,1]
	s_nop 0
	v_exp_f32_e32 v122, v122
	v_exp_f32_e32 v123, v123
	s_nop 0
	v_pk_add_f32 v[122:123], v[122:123], v[188:189]
	s_nop 0
	v_rcp_f32_e32 v122, v122
	v_rcp_f32_e32 v123, v123
	s_nop 0
	s_nop 0
	v_pk_mul_f32 v[124:125], v[124:125], v[122:123]
.LBB0_270:
	v_and_b32_e32 v123, 16, v0
	v_lshrrev_b32_e32 v0, 2, v0
	v_cvt_pk_bf16_f32 v126, v126, v127
	v_cvt_pk_bf16_f32 v127, v128, v129
	v_lshl_or_b32 v122, v138, 5, s25
	v_and_b32_e32 v0, 8, v0
	v_mad_u64_u32 v[128:129], s[10:11], v130, s22, 0
	v_or3_b32 v122, v122, v123, v0
	v_mov_b32_e32 v0, v129
	v_mad_u64_u32 v[138:139], s[10:11], v131, s22, v[0:1]
	v_mov_b32_e32 v129, v138
	v_lshl_add_u64 v[138:139], v[128:129], 1, s[6:7]
	v_cvt_pk_bf16_f32 v128, v136, v137
	v_cvt_pk_bf16_f32 v129, v124, v125
	v_ashrrev_i32_e32 v123, 31, v122
	v_permlane16_swap_b32_e32 v126, v128
	v_permlane16_swap_b32_e32 v127, v129
	v_lshl_add_u64 v[124:125], v[122:123], 1, v[138:139]
	v_pk_mul_f32 v[118:119], v[118:119], v[134:135]
	s_and_b64 vcc, exec, s[4:5]
	v_pk_mul_f32 v[120:121], v[120:121], v[134:135]
	global_store_dwordx4 v[124:125], v[126:129], off
	s_cbranch_vccnz .LBB0_272
	s_nop 0
	v_pk_mul_f32 v[126:127], v[118:119], v[118:119]
	s_nop 0
	s_nop 0
	s_nop 0
	v_pk_fma_f32 v[126:127], v[126:127], v[184:185], v[186:187]
	s_nop 0
	v_pk_mul_f32 v[126:127], v[126:127], v[118:119] neg_lo:[0,1] neg_hi:[0,1]
	s_nop 0
	v_exp_f32_e32 v126, v126
	v_exp_f32_e32 v127, v127
	s_nop 0
	v_pk_add_f32 v[126:127], v[126:127], v[188:189]
	s_nop 0
	v_rcp_f32_e32 v126, v126
	v_rcp_f32_e32 v127, v127
	s_nop 0
	s_nop 0
	v_pk_mul_f32 v[118:119], v[118:119], v[126:127]
	v_pk_mul_f32 v[126:127], v[120:121], v[120:121]
	s_nop 0
	s_nop 0
	s_nop 0
	v_pk_fma_f32 v[126:127], v[126:127], v[184:185], v[186:187]
	s_nop 0
	v_pk_mul_f32 v[126:127], v[126:127], v[120:121] neg_lo:[0,1] neg_hi:[0,1]
	s_nop 0
	v_exp_f32_e32 v126, v126
	v_exp_f32_e32 v127, v127
	s_nop 0
	v_pk_add_f32 v[126:127], v[126:127], v[188:189]
	s_nop 0
	v_rcp_f32_e32 v126, v126
	v_rcp_f32_e32 v127, v127
	s_nop 0
	s_nop 0
	v_pk_mul_f32 v[120:121], v[120:121], v[126:127]
.LBB0_272:
	v_pk_mul_f32 v[114:115], v[114:115], v[134:135]
	s_and_b64 vcc, exec, s[4:5]
	v_pk_mul_f32 v[116:117], v[116:117], v[134:135]
	s_cbranch_vccnz .LBB0_274
	v_pk_mul_f32 v[126:127], v[114:115], v[114:115]
	s_nop 0
	s_nop 0
	s_nop 0
	v_pk_fma_f32 v[126:127], v[126:127], v[184:185], v[186:187]
	s_nop 0
	v_pk_mul_f32 v[126:127], v[126:127], v[114:115] neg_lo:[0,1] neg_hi:[0,1]
	s_nop 0
	v_exp_f32_e32 v126, v126
	v_exp_f32_e32 v127, v127
	s_nop 0
	v_pk_add_f32 v[126:127], v[126:127], v[188:189]
	s_nop 0
	v_rcp_f32_e32 v126, v126
	v_rcp_f32_e32 v127, v127
	s_nop 0
	s_nop 0
	v_pk_mul_f32 v[114:115], v[114:115], v[126:127]
	v_pk_mul_f32 v[126:127], v[116:117], v[116:117]
	s_nop 0
	s_nop 0
	s_nop 0
	v_pk_fma_f32 v[126:127], v[126:127], v[184:185], v[186:187]
	s_nop 0
	v_pk_mul_f32 v[126:127], v[126:127], v[116:117] neg_lo:[0,1] neg_hi:[0,1]
	s_nop 0
	v_exp_f32_e32 v126, v126
	v_exp_f32_e32 v127, v127
	s_nop 0
	v_pk_add_f32 v[126:127], v[126:127], v[188:189]
	s_nop 0
	v_rcp_f32_e32 v126, v126
	v_rcp_f32_e32 v127, v127
	s_nop 0
	s_nop 0
	v_pk_mul_f32 v[116:117], v[116:117], v[126:127]
; __device__ __forceinline__ float gelu_f(float x) {
;   const float c2 = 2.f * 0.7978845608028654f * 1.4426950408889634f;
;   float p = __builtin_fmaf(x * x, 0.044715f * c2, c2);
;   float e = __builtin_amdgcn_exp2f(-x * p);
;   return x * __builtin_amdgcn_rcpf(1.f + e);
; }
; template <int MODE>
; __device__ __forceinline__ void gemm_tile(const int ph, const int which, const int pm, const int pn) {
;     ...
;   for (int ai = 0; ai < 2; ++ai)
;     for (int m = 0; m < 4; ++m) {
;       const int row = browC + ai * HALF + wr * 64 + m * 16 + fr;
;       float s = 1.f;
;       if (MODE == 1) s = scale[row];
;       for (int bj = 0; bj < 2; ++bj) {
;         uint2 o[2];
; #pragma unroll
;         for (int n = 0; n < 2; ++n) {
;           const int col = ecol + bj * HALF + wc * 32 + n * 16 + fq * 4;
;           f32x4 v = acc[ai][bj][m][n];
;           float x0, x1, x2, x3;
;           if (MODE == 2) {
;             float4 c4 = *(const float4*)(scale + col);
;             x0 = v[0] * c4.x; x1 = v[1] * c4.y; x2 = v[2] * c4.z; x3 = v[3] * c4.w;
;           } else {
;             x0 = v[0] * s; x1 = v[1] * s; x2 = v[2] * s; x3 = v[3] * s;
;           }
;           if (MODE == 1 && act) { x0 = gelu_f(x0); x1 = gelu_f(x1); x2 = gelu_f(x2); x3 = gelu_f(x3); }
;           o[n].x = pack2(x0, x1);
;           o[n].y = pack2(x2, x3);
;         }
;         auto rx = __builtin_amdgcn_permlane16_swap(o[0].x, o[1].x, false, false);
;         auto ry = __builtin_amdgcn_permlane16_swap(o[0].y, o[1].y, false, false);
;         const int colw = ecol + bj * HALF + wc * 32 + (fq & 1) * 16 + (fq >> 1) * 8;
;         *(uint4*)(C + (size_t)row * ldc + colw) = make_uint4(rx[0], ry[0], rx[1], ry[1]);
;       }
;     }
.LBB0_274:
	v_cvt_pk_bf16_f32 v118, v118, v119
	v_cvt_pk_bf16_f32 v119, v120, v121
	v_cvt_pk_bf16_f32 v120, v114, v115
	v_cvt_pk_bf16_f32 v121, v116, v117
	s_nop 0
	v_permlane16_swap_b32_e32 v118, v120
	v_permlane16_swap_b32_e32 v119, v121
	global_store_dwordx4 v[124:125], v[118:121], off offset:256
	s_and_b64 vcc, exec, s[4:5]
	v_mov_b32_e32 v114, v177
	v_pk_mul_f32 v[110:111], v[110:111], v[114:115] op_sel_hi:[1,0]
	v_pk_mul_f32 v[112:113], v[112:113], v[114:115] op_sel_hi:[1,0]
	s_cbranch_vccnz .LBB0_276
	v_pk_mul_f32 v[116:117], v[110:111], v[110:111]
	s_nop 0
	s_nop 0
	s_nop 0
	v_pk_fma_f32 v[116:117], v[116:117], v[184:185], v[186:187]
	s_nop 0
	v_pk_mul_f32 v[116:117], v[116:117], v[110:111] neg_lo:[0,1] neg_hi:[0,1]
	s_nop 0
	v_exp_f32_e32 v116, v116
	v_exp_f32_e32 v117, v117
	s_nop 0
	v_pk_add_f32 v[116:117], v[116:117], v[188:189]
	s_nop 0
	v_rcp_f32_e32 v116, v116
	v_rcp_f32_e32 v117, v117
	s_nop 0
	s_nop 0
	v_pk_mul_f32 v[110:111], v[110:111], v[116:117]
	v_pk_mul_f32 v[116:117], v[112:113], v[112:113]
	s_nop 0
	s_nop 0
	s_nop 0
	v_pk_fma_f32 v[116:117], v[116:117], v[184:185], v[186:187]
	s_nop 0
	v_pk_mul_f32 v[116:117], v[116:117], v[112:113] neg_lo:[0,1] neg_hi:[0,1]
	s_nop 0
	v_exp_f32_e32 v116, v116
	v_exp_f32_e32 v117, v117
	s_nop 0
	v_pk_add_f32 v[116:117], v[116:117], v[188:189]
	s_nop 0
	v_rcp_f32_e32 v116, v116
	v_rcp_f32_e32 v117, v117
	s_nop 0
	s_nop 0
	v_pk_mul_f32 v[112:113], v[112:113], v[116:117]
.LBB0_276:
	v_mov_b32_e32 v115, v114
	v_pk_mul_f32 v[106:107], v[106:107], v[114:115]
	s_and_b64 vcc, exec, s[4:5]
	v_pk_mul_f32 v[108:109], v[108:109], v[114:115]
	s_cbranch_vccnz .LBB0_278
	v_pk_mul_f32 v[116:117], v[106:107], v[106:107]
	s_nop 0
	s_nop 0
	s_nop 0
	v_pk_fma_f32 v[116:117], v[116:117], v[184:185], v[186:187]
	s_nop 0
	v_pk_mul_f32 v[116:117], v[116:117], v[106:107] neg_lo:[0,1] neg_hi:[0,1]
	s_nop 0
	v_exp_f32_e32 v116, v116
	v_exp_f32_e32 v117, v117
	s_nop 0
	v_pk_add_f32 v[116:117], v[116:117], v[188:189]
	s_nop 0
	v_rcp_f32_e32 v116, v116
	v_rcp_f32_e32 v117, v117
	s_nop 0
	s_nop 0
	v_pk_mul_f32 v[106:107], v[106:107], v[116:117]
	v_pk_mul_f32 v[116:117], v[108:109], v[108:109]
	s_nop 0
	s_nop 0
	s_nop 0
	v_pk_fma_f32 v[116:117], v[116:117], v[184:185], v[186:187]
	s_nop 0
	v_pk_mul_f32 v[116:117], v[116:117], v[108:109] neg_lo:[0,1] neg_hi:[0,1]
	s_nop 0
	v_exp_f32_e32 v116, v116
	v_exp_f32_e32 v117, v117
	s_nop 0
	v_pk_add_f32 v[116:117], v[116:117], v[188:189]
	s_nop 0
	v_rcp_f32_e32 v116, v116
	v_rcp_f32_e32 v117, v117
	s_nop 0
	s_nop 0
	v_pk_mul_f32 v[108:109], v[108:109], v[116:117]
.LBB0_278:
	v_add_u32_e32 v0, 16, v130
	v_cvt_pk_bf16_f32 v110, v110, v111
	v_cvt_pk_bf16_f32 v111, v112, v113
	v_mad_u64_u32 v[112:113], s[10:11], v0, s22, 0
	v_ashrrev_i32_e32 v116, 31, v0
	v_mov_b32_e32 v0, v113
	v_mad_u64_u32 v[116:117], s[10:11], v116, s22, v[0:1]
	v_mov_b32_e32 v113, v116
	v_lshl_add_u64 v[116:117], v[112:113], 1, s[6:7]
	v_cvt_pk_bf16_f32 v112, v106, v107
	v_cvt_pk_bf16_f32 v113, v108, v109
	s_nop 0
	v_permlane16_swap_b32_e32 v110, v112
	v_permlane16_swap_b32_e32 v111, v113
	v_lshl_add_u64 v[106:107], v[122:123], 1, v[116:117]
	v_pk_mul_f32 v[102:103], v[102:103], v[114:115]
	s_and_b64 vcc, exec, s[4:5]
	v_pk_mul_f32 v[104:105], v[104:105], v[114:115]
	global_store_dwordx4 v[106:107], v[110:113], off
	s_cbranch_vccnz .LBB0_280
	v_pk_mul_f32 v[108:109], v[102:103], v[102:103]
	s_nop 0
	s_nop 0
	s_nop 0
	v_pk_fma_f32 v[108:109], v[108:109], v[184:185], v[186:187]
	s_nop 0
	v_pk_mul_f32 v[108:109], v[108:109], v[102:103] neg_lo:[0,1] neg_hi:[0,1]
	s_nop 0
	v_exp_f32_e32 v108, v108
	v_exp_f32_e32 v109, v109
	s_nop 0
	v_pk_add_f32 v[108:109], v[108:109], v[188:189]
	s_nop 0
	v_rcp_f32_e32 v108, v108
	v_rcp_f32_e32 v109, v109
	s_nop 0
	s_nop 0
	v_pk_mul_f32 v[102:103], v[102:103], v[108:109]
	v_pk_mul_f32 v[108:109], v[104:105], v[104:105]
	s_nop 0
	s_nop 0
	s_nop 0
	v_pk_fma_f32 v[108:109], v[108:109], v[184:185], v[186:187]
	s_nop 0
	v_pk_mul_f32 v[108:109], v[108:109], v[104:105] neg_lo:[0,1] neg_hi:[0,1]
	s_nop 0
	v_exp_f32_e32 v108, v108
	v_exp_f32_e32 v109, v109
	s_nop 0
	v_pk_add_f32 v[108:109], v[108:109], v[188:189]
	s_nop 0
	v_rcp_f32_e32 v108, v108
	v_rcp_f32_e32 v109, v109
	s_nop 0
	s_nop 0
	v_pk_mul_f32 v[104:105], v[104:105], v[108:109]
.LBB0_280:
	v_pk_mul_f32 v[98:99], v[98:99], v[114:115]
	s_and_b64 vcc, exec, s[4:5]
	v_pk_mul_f32 v[100:101], v[100:101], v[114:115]
	s_cbranch_vccnz .LBB0_282
	v_pk_mul_f32 v[108:109], v[98:99], v[98:99]
	s_nop 0
	s_nop 0
	s_nop 0
	v_pk_fma_f32 v[108:109], v[108:109], v[184:185], v[186:187]
	s_nop 0
	v_pk_mul_f32 v[108:109], v[108:109], v[98:99] neg_lo:[0,1] neg_hi:[0,1]
	s_nop 0
	v_exp_f32_e32 v108, v108
	v_exp_f32_e32 v109, v109
	s_nop 0
	v_pk_add_f32 v[108:109], v[108:109], v[188:189]
	s_nop 0
	v_rcp_f32_e32 v108, v108
	v_rcp_f32_e32 v109, v109
	s_nop 0
	s_nop 0
	v_pk_mul_f32 v[98:99], v[98:99], v[108:109]
	v_pk_mul_f32 v[108:109], v[100:101], v[100:101]
	s_nop 0
	s_nop 0
	s_nop 0
	v_pk_fma_f32 v[108:109], v[108:109], v[184:185], v[186:187]
	s_nop 0
	v_pk_mul_f32 v[108:109], v[108:109], v[100:101] neg_lo:[0,1] neg_hi:[0,1]
	s_nop 0
	v_exp_f32_e32 v108, v108
	v_exp_f32_e32 v109, v109
	s_nop 0
	v_pk_add_f32 v[108:109], v[108:109], v[188:189]
	s_nop 0
	v_rcp_f32_e32 v108, v108
	v_rcp_f32_e32 v109, v109
	s_nop 0
	s_nop 0
	v_pk_mul_f32 v[100:101], v[100:101], v[108:109]
; __device__ __forceinline__ float gelu_f(float x) {
;   const float c2 = 2.f * 0.7978845608028654f * 1.4426950408889634f;
;   float p = __builtin_fmaf(x * x, 0.044715f * c2, c2);
;   float e = __builtin_amdgcn_exp2f(-x * p);
;   return x * __builtin_amdgcn_rcpf(1.f + e);
; }
; template <int MODE>
; __device__ __forceinline__ void gemm_tile(const int ph, const int which, const int pm, const int pn) {
;     ...
;   for (int ai = 0; ai < 2; ++ai)
;     for (int m = 0; m < 4; ++m) {
;       const int row = browC + ai * HALF + wr * 64 + m * 16 + fr;
;       float s = 1.f;
;       if (MODE == 1) s = scale[row];
;       for (int bj = 0; bj < 2; ++bj) {
;         uint2 o[2];
; #pragma unroll
;         for (int n = 0; n < 2; ++n) {
;           const int col = ecol + bj * HALF + wc * 32 + n * 16 + fq * 4;
;           f32x4 v = acc[ai][bj][m][n];
;           float x0, x1, x2, x3;
;           if (MODE == 2) {
;             float4 c4 = *(const float4*)(scale + col);
;             x0 = v[0] * c4.x; x1 = v[1] * c4.y; x2 = v[2] * c4.z; x3 = v[3] * c4.w;
;           } else {
;             x0 = v[0] * s; x1 = v[1] * s; x2 = v[2] * s; x3 = v[3] * s;
;           }
;           if (MODE == 1 && act) { x0 = gelu_f(x0); x1 = gelu_f(x1); x2 = gelu_f(x2); x3 = gelu_f(x3); }
;           o[n].x = pack2(x0, x1);
;           o[n].y = pack2(x2, x3);
;         }
;         auto rx = __builtin_amdgcn_permlane16_swap(o[0].x, o[1].x, false, false);
;         auto ry = __builtin_amdgcn_permlane16_swap(o[0].y, o[1].y, false, false);
;         const int colw = ecol + bj * HALF + wc * 32 + (fq & 1) * 16 + (fq >> 1) * 8;
;         *(uint4*)(C + (size_t)row * ldc + colw) = make_uint4(rx[0], ry[0], rx[1], ry[1]);
;       }
;     }
.LBB0_282:
	v_cvt_pk_bf16_f32 v102, v102, v103
	v_cvt_pk_bf16_f32 v103, v104, v105
	v_cvt_pk_bf16_f32 v104, v98, v99
	v_cvt_pk_bf16_f32 v105, v100, v101
	s_nop 0
	v_permlane16_swap_b32_e32 v102, v104
	v_permlane16_swap_b32_e32 v103, v105
	global_store_dwordx4 v[106:107], v[102:105], off offset:256
	s_and_b64 vcc, exec, s[4:5]
	v_mov_b32_e32 v98, v178
	v_pk_mul_f32 v[94:95], v[94:95], v[98:99] op_sel_hi:[1,0]
	v_pk_mul_f32 v[96:97], v[96:97], v[98:99] op_sel_hi:[1,0]
	s_cbranch_vccnz .LBB0_284
	v_pk_mul_f32 v[100:101], v[94:95], v[94:95]
	s_nop 0
	s_nop 0
	s_nop 0
	v_pk_fma_f32 v[100:101], v[100:101], v[184:185], v[186:187]
	s_nop 0
	v_pk_mul_f32 v[100:101], v[100:101], v[94:95] neg_lo:[0,1] neg_hi:[0,1]
	s_nop 0
	v_exp_f32_e32 v100, v100
	v_exp_f32_e32 v101, v101
	s_nop 0
	v_pk_add_f32 v[100:101], v[100:101], v[188:189]
	s_nop 0
	v_rcp_f32_e32 v100, v100
	v_rcp_f32_e32 v101, v101
	s_nop 0
	s_nop 0
	v_pk_mul_f32 v[94:95], v[94:95], v[100:101]
	v_pk_mul_f32 v[100:101], v[96:97], v[96:97]
	s_nop 0
	s_nop 0
	s_nop 0
	v_pk_fma_f32 v[100:101], v[100:101], v[184:185], v[186:187]
	s_nop 0
	v_pk_mul_f32 v[100:101], v[100:101], v[96:97] neg_lo:[0,1] neg_hi:[0,1]
	s_nop 0
	v_exp_f32_e32 v100, v100
	v_exp_f32_e32 v101, v101
	s_nop 0
	v_pk_add_f32 v[100:101], v[100:101], v[188:189]
	s_nop 0
	v_rcp_f32_e32 v100, v100
	v_rcp_f32_e32 v101, v101
	s_nop 0
	s_nop 0
	v_pk_mul_f32 v[96:97], v[96:97], v[100:101]
.LBB0_284:
	v_mov_b32_e32 v99, v98
	v_pk_mul_f32 v[90:91], v[90:91], v[98:99]
	s_and_b64 vcc, exec, s[4:5]
	v_pk_mul_f32 v[92:93], v[92:93], v[98:99]
	s_cbranch_vccnz .LBB0_286
	v_pk_mul_f32 v[100:101], v[90:91], v[90:91]
	s_nop 0
	s_nop 0
	s_nop 0
	v_pk_fma_f32 v[100:101], v[100:101], v[184:185], v[186:187]
	s_nop 0
	v_pk_mul_f32 v[100:101], v[100:101], v[90:91] neg_lo:[0,1] neg_hi:[0,1]
	s_nop 0
	v_exp_f32_e32 v100, v100
	v_exp_f32_e32 v101, v101
	s_nop 0
	v_pk_add_f32 v[100:101], v[100:101], v[188:189]
	s_nop 0
	v_rcp_f32_e32 v100, v100
	v_rcp_f32_e32 v101, v101
	s_nop 0
	s_nop 0
	v_pk_mul_f32 v[90:91], v[90:91], v[100:101]
	v_pk_mul_f32 v[100:101], v[92:93], v[92:93]
	s_nop 0
	s_nop 0
	s_nop 0
	v_pk_fma_f32 v[100:101], v[100:101], v[184:185], v[186:187]
	s_nop 0
	v_pk_mul_f32 v[100:101], v[100:101], v[92:93] neg_lo:[0,1] neg_hi:[0,1]
	s_nop 0
	v_exp_f32_e32 v100, v100
	v_exp_f32_e32 v101, v101
	s_nop 0
	v_pk_add_f32 v[100:101], v[100:101], v[188:189]
	s_nop 0
	v_rcp_f32_e32 v100, v100
	v_rcp_f32_e32 v101, v101
	s_nop 0
	s_nop 0
	v_pk_mul_f32 v[92:93], v[92:93], v[100:101]
.LBB0_286:
	v_add_u32_e32 v0, 32, v130
	v_cvt_pk_bf16_f32 v94, v94, v95
	v_cvt_pk_bf16_f32 v95, v96, v97
	v_mad_u64_u32 v[96:97], s[10:11], v0, s22, 0
	v_ashrrev_i32_e32 v100, 31, v0
	v_mov_b32_e32 v0, v97
	v_mad_u64_u32 v[100:101], s[10:11], v100, s22, v[0:1]
	v_mov_b32_e32 v97, v100
	v_lshl_add_u64 v[100:101], v[96:97], 1, s[6:7]
	v_cvt_pk_bf16_f32 v96, v90, v91
	v_cvt_pk_bf16_f32 v97, v92, v93
	s_nop 0
	v_permlane16_swap_b32_e32 v94, v96
	v_permlane16_swap_b32_e32 v95, v97
	v_lshl_add_u64 v[90:91], v[122:123], 1, v[100:101]
	v_pk_mul_f32 v[86:87], v[86:87], v[98:99]
	s_and_b64 vcc, exec, s[4:5]
	v_pk_mul_f32 v[88:89], v[88:89], v[98:99]
	global_store_dwordx4 v[90:91], v[94:97], off
	s_cbranch_vccnz .LBB0_288
	v_pk_mul_f32 v[92:93], v[86:87], v[86:87]
	s_nop 0
	s_nop 0
	s_nop 0
	v_pk_fma_f32 v[92:93], v[92:93], v[184:185], v[186:187]
	s_nop 0
	v_pk_mul_f32 v[92:93], v[92:93], v[86:87] neg_lo:[0,1] neg_hi:[0,1]
	s_nop 0
	v_exp_f32_e32 v92, v92
	v_exp_f32_e32 v93, v93
	s_nop 0
	v_pk_add_f32 v[92:93], v[92:93], v[188:189]
	s_nop 0
	v_rcp_f32_e32 v92, v92
	v_rcp_f32_e32 v93, v93
	s_nop 0
	s_nop 0
	v_pk_mul_f32 v[86:87], v[86:87], v[92:93]
	v_pk_mul_f32 v[92:93], v[88:89], v[88:89]
	s_nop 0
	s_nop 0
	s_nop 0
	v_pk_fma_f32 v[92:93], v[92:93], v[184:185], v[186:187]
	s_nop 0
	v_pk_mul_f32 v[92:93], v[92:93], v[88:89] neg_lo:[0,1] neg_hi:[0,1]
	s_nop 0
	v_exp_f32_e32 v92, v92
	v_exp_f32_e32 v93, v93
	s_nop 0
	v_pk_add_f32 v[92:93], v[92:93], v[188:189]
	s_nop 0
	v_rcp_f32_e32 v92, v92
	v_rcp_f32_e32 v93, v93
	s_nop 0
	s_nop 0
	v_pk_mul_f32 v[88:89], v[88:89], v[92:93]
.LBB0_288:
	v_pk_mul_f32 v[82:83], v[82:83], v[98:99]
	s_and_b64 vcc, exec, s[4:5]
	v_pk_mul_f32 v[84:85], v[84:85], v[98:99]
	s_cbranch_vccnz .LBB0_290
	v_pk_mul_f32 v[92:93], v[82:83], v[82:83]
	s_nop 0
	s_nop 0
	s_nop 0
	v_pk_fma_f32 v[92:93], v[92:93], v[184:185], v[186:187]
	s_nop 0
	v_pk_mul_f32 v[92:93], v[92:93], v[82:83] neg_lo:[0,1] neg_hi:[0,1]
	s_nop 0
	v_exp_f32_e32 v92, v92
	v_exp_f32_e32 v93, v93
	s_nop 0
	v_pk_add_f32 v[92:93], v[92:93], v[188:189]
	s_nop 0
	v_rcp_f32_e32 v92, v92
	v_rcp_f32_e32 v93, v93
	s_nop 0
	s_nop 0
	v_pk_mul_f32 v[82:83], v[82:83], v[92:93]
	v_pk_mul_f32 v[92:93], v[84:85], v[84:85]
	s_nop 0
	s_nop 0
	s_nop 0
	v_pk_fma_f32 v[92:93], v[92:93], v[184:185], v[186:187]
	s_nop 0
	v_pk_mul_f32 v[92:93], v[92:93], v[84:85] neg_lo:[0,1] neg_hi:[0,1]
	s_nop 0
	v_exp_f32_e32 v92, v92
	v_exp_f32_e32 v93, v93
	s_nop 0
	v_pk_add_f32 v[92:93], v[92:93], v[188:189]
	s_nop 0
	v_rcp_f32_e32 v92, v92
	v_rcp_f32_e32 v93, v93
	s_nop 0
	s_nop 0
	v_pk_mul_f32 v[84:85], v[84:85], v[92:93]
; __device__ __forceinline__ float gelu_f(float x) {
;   const float c2 = 2.f * 0.7978845608028654f * 1.4426950408889634f;
;   float p = __builtin_fmaf(x * x, 0.044715f * c2, c2);
;   float e = __builtin_amdgcn_exp2f(-x * p);
;   return x * __builtin_amdgcn_rcpf(1.f + e);
; }
; template <int MODE>
; __device__ __forceinline__ void gemm_tile(const int ph, const int which, const int pm, const int pn) {
;     ...
;   for (int ai = 0; ai < 2; ++ai)
;     for (int m = 0; m < 4; ++m) {
;       const int row = browC + ai * HALF + wr * 64 + m * 16 + fr;
;       float s = 1.f;
;       if (MODE == 1) s = scale[row];
;       for (int bj = 0; bj < 2; ++bj) {
;         uint2 o[2];
; #pragma unroll
;         for (int n = 0; n < 2; ++n) {
;           const int col = ecol + bj * HALF + wc * 32 + n * 16 + fq * 4;
;           f32x4 v = acc[ai][bj][m][n];
;           float x0, x1, x2, x3;
;           if (MODE == 2) {
;             float4 c4 = *(const float4*)(scale + col);
;             x0 = v[0] * c4.x; x1 = v[1] * c4.y; x2 = v[2] * c4.z; x3 = v[3] * c4.w;
;           } else {
;             x0 = v[0] * s; x1 = v[1] * s; x2 = v[2] * s; x3 = v[3] * s;
;           }
;           if (MODE == 1 && act) { x0 = gelu_f(x0); x1 = gelu_f(x1); x2 = gelu_f(x2); x3 = gelu_f(x3); }
;           o[n].x = pack2(x0, x1);
;           o[n].y = pack2(x2, x3);
;         }
;         auto rx = __builtin_amdgcn_permlane16_swap(o[0].x, o[1].x, false, false);
;         auto ry = __builtin_amdgcn_permlane16_swap(o[0].y, o[1].y, false, false);
;         const int colw = ecol + bj * HALF + wc * 32 + (fq & 1) * 16 + (fq >> 1) * 8;
;         *(uint4*)(C + (size_t)row * ldc + colw) = make_uint4(rx[0], ry[0], rx[1], ry[1]);
;       }
;     }
.LBB0_290:
	v_cvt_pk_bf16_f32 v86, v86, v87
	v_cvt_pk_bf16_f32 v87, v88, v89
	v_cvt_pk_bf16_f32 v88, v82, v83
	v_cvt_pk_bf16_f32 v89, v84, v85
	s_nop 0
	v_permlane16_swap_b32_e32 v86, v88
	v_permlane16_swap_b32_e32 v87, v89
	global_store_dwordx4 v[90:91], v[86:89], off offset:256
	s_and_b64 vcc, exec, s[4:5]
	v_mov_b32_e32 v82, v179
	v_pk_mul_f32 v[78:79], v[78:79], v[82:83] op_sel_hi:[1,0]
	v_pk_mul_f32 v[80:81], v[80:81], v[82:83] op_sel_hi:[1,0]
	s_cbranch_vccnz .LBB0_292
	v_pk_mul_f32 v[84:85], v[78:79], v[78:79]
	s_nop 0
	s_nop 0
	s_nop 0
	v_pk_fma_f32 v[84:85], v[84:85], v[184:185], v[186:187]
	s_nop 0
	v_pk_mul_f32 v[84:85], v[84:85], v[78:79] neg_lo:[0,1] neg_hi:[0,1]
	s_nop 0
	v_exp_f32_e32 v84, v84
	v_exp_f32_e32 v85, v85
	s_nop 0
	v_pk_add_f32 v[84:85], v[84:85], v[188:189]
	s_nop 0
	v_rcp_f32_e32 v84, v84
	v_rcp_f32_e32 v85, v85
	s_nop 0
	s_nop 0
	v_pk_mul_f32 v[78:79], v[78:79], v[84:85]
	v_pk_mul_f32 v[84:85], v[80:81], v[80:81]
	s_nop 0
	s_nop 0
	s_nop 0
	v_pk_fma_f32 v[84:85], v[84:85], v[184:185], v[186:187]
	s_nop 0
	v_pk_mul_f32 v[84:85], v[84:85], v[80:81] neg_lo:[0,1] neg_hi:[0,1]
	s_nop 0
	v_exp_f32_e32 v84, v84
	v_exp_f32_e32 v85, v85
	s_nop 0
	v_pk_add_f32 v[84:85], v[84:85], v[188:189]
	s_nop 0
	v_rcp_f32_e32 v84, v84
	v_rcp_f32_e32 v85, v85
	s_nop 0
	s_nop 0
	v_pk_mul_f32 v[80:81], v[80:81], v[84:85]
.LBB0_292:
	v_mov_b32_e32 v83, v82
	v_pk_mul_f32 v[74:75], v[74:75], v[82:83]
	s_and_b64 vcc, exec, s[4:5]
	v_pk_mul_f32 v[76:77], v[76:77], v[82:83]
	s_cbranch_vccnz .LBB0_294
	v_pk_mul_f32 v[84:85], v[74:75], v[74:75]
	s_nop 0
	s_nop 0
	s_nop 0
	v_pk_fma_f32 v[84:85], v[84:85], v[184:185], v[186:187]
	s_nop 0
	v_pk_mul_f32 v[84:85], v[84:85], v[74:75] neg_lo:[0,1] neg_hi:[0,1]
	s_nop 0
	v_exp_f32_e32 v84, v84
	v_exp_f32_e32 v85, v85
	s_nop 0
	v_pk_add_f32 v[84:85], v[84:85], v[188:189]
	s_nop 0
	v_rcp_f32_e32 v84, v84
	v_rcp_f32_e32 v85, v85
	s_nop 0
	s_nop 0
	v_pk_mul_f32 v[74:75], v[74:75], v[84:85]
	v_pk_mul_f32 v[84:85], v[76:77], v[76:77]
	s_nop 0
	s_nop 0
	s_nop 0
	v_pk_fma_f32 v[84:85], v[84:85], v[184:185], v[186:187]
	s_nop 0
	v_pk_mul_f32 v[84:85], v[84:85], v[76:77] neg_lo:[0,1] neg_hi:[0,1]
	s_nop 0
	v_exp_f32_e32 v84, v84
	v_exp_f32_e32 v85, v85
	s_nop 0
	v_pk_add_f32 v[84:85], v[84:85], v[188:189]
	s_nop 0
	v_rcp_f32_e32 v84, v84
	v_rcp_f32_e32 v85, v85
	s_nop 0
	s_nop 0
	v_pk_mul_f32 v[76:77], v[76:77], v[84:85]
.LBB0_294:
	v_add_u32_e32 v0, 48, v130
	v_cvt_pk_bf16_f32 v78, v78, v79
	v_cvt_pk_bf16_f32 v79, v80, v81
	v_mad_u64_u32 v[80:81], s[10:11], v0, s22, 0
	v_ashrrev_i32_e32 v84, 31, v0
	v_mov_b32_e32 v0, v81
	v_mad_u64_u32 v[84:85], s[10:11], v84, s22, v[0:1]
	v_mov_b32_e32 v81, v84
	v_lshl_add_u64 v[84:85], v[80:81], 1, s[6:7]
	v_cvt_pk_bf16_f32 v80, v74, v75
	v_cvt_pk_bf16_f32 v81, v76, v77
	s_nop 0
	v_permlane16_swap_b32_e32 v78, v80
	v_permlane16_swap_b32_e32 v79, v81
	v_lshl_add_u64 v[74:75], v[122:123], 1, v[84:85]
	v_pk_mul_f32 v[70:71], v[70:71], v[82:83]
	s_and_b64 vcc, exec, s[4:5]
	v_pk_mul_f32 v[72:73], v[72:73], v[82:83]
	global_store_dwordx4 v[74:75], v[78:81], off
	s_cbranch_vccnz .LBB0_296
	v_pk_mul_f32 v[76:77], v[70:71], v[70:71]
	s_nop 0
	s_nop 0
	s_nop 0
	v_pk_fma_f32 v[76:77], v[76:77], v[184:185], v[186:187]
	s_nop 0
	v_pk_mul_f32 v[76:77], v[76:77], v[70:71] neg_lo:[0,1] neg_hi:[0,1]
	s_nop 0
	v_exp_f32_e32 v76, v76
	v_exp_f32_e32 v77, v77
	s_nop 0
	v_pk_add_f32 v[76:77], v[76:77], v[188:189]
	s_nop 0
	v_rcp_f32_e32 v76, v76
	v_rcp_f32_e32 v77, v77
	s_nop 0
	s_nop 0
	v_pk_mul_f32 v[70:71], v[70:71], v[76:77]
	v_pk_mul_f32 v[76:77], v[72:73], v[72:73]
	s_nop 0
	s_nop 0
	s_nop 0
	v_pk_fma_f32 v[76:77], v[76:77], v[184:185], v[186:187]
	s_nop 0
	v_pk_mul_f32 v[76:77], v[76:77], v[72:73] neg_lo:[0,1] neg_hi:[0,1]
	s_nop 0
	v_exp_f32_e32 v76, v76
	v_exp_f32_e32 v77, v77
	s_nop 0
	v_pk_add_f32 v[76:77], v[76:77], v[188:189]
	s_nop 0
	v_rcp_f32_e32 v76, v76
	v_rcp_f32_e32 v77, v77
	s_nop 0
	s_nop 0
	v_pk_mul_f32 v[72:73], v[72:73], v[76:77]
.LBB0_296:
	v_pk_mul_f32 v[66:67], v[66:67], v[82:83]
	s_and_b64 vcc, exec, s[4:5]
	v_pk_mul_f32 v[68:69], v[68:69], v[82:83]
	s_cbranch_vccnz .LBB0_298
	v_pk_mul_f32 v[76:77], v[66:67], v[66:67]
	s_nop 0
	s_nop 0
	s_nop 0
	v_pk_fma_f32 v[76:77], v[76:77], v[184:185], v[186:187]
	s_nop 0
	v_pk_mul_f32 v[76:77], v[76:77], v[66:67] neg_lo:[0,1] neg_hi:[0,1]
	s_nop 0
	v_exp_f32_e32 v76, v76
	v_exp_f32_e32 v77, v77
	s_nop 0
	v_pk_add_f32 v[76:77], v[76:77], v[188:189]
	s_nop 0
	v_rcp_f32_e32 v76, v76
	v_rcp_f32_e32 v77, v77
	s_nop 0
	s_nop 0
	v_pk_mul_f32 v[66:67], v[66:67], v[76:77]
	v_pk_mul_f32 v[76:77], v[68:69], v[68:69]
	s_nop 0
	s_nop 0
	s_nop 0
	v_pk_fma_f32 v[76:77], v[76:77], v[184:185], v[186:187]
	s_nop 0
	v_pk_mul_f32 v[76:77], v[76:77], v[68:69] neg_lo:[0,1] neg_hi:[0,1]
	s_nop 0
	v_exp_f32_e32 v76, v76
	v_exp_f32_e32 v77, v77
	s_nop 0
	v_pk_add_f32 v[76:77], v[76:77], v[188:189]
	s_nop 0
	v_rcp_f32_e32 v76, v76
	v_rcp_f32_e32 v77, v77
	s_nop 0
	s_nop 0
	v_pk_mul_f32 v[68:69], v[68:69], v[76:77]
; __device__ __forceinline__ float gelu_f(float x) {
;   const float c2 = 2.f * 0.7978845608028654f * 1.4426950408889634f;
;   float p = __builtin_fmaf(x * x, 0.044715f * c2, c2);
;   float e = __builtin_amdgcn_exp2f(-x * p);
;   return x * __builtin_amdgcn_rcpf(1.f + e);
; }
; template <int MODE>
; __device__ __forceinline__ void gemm_tile(const int ph, const int which, const int pm, const int pn) {
;     ...
;   for (int ai = 0; ai < 2; ++ai)
;     for (int m = 0; m < 4; ++m) {
;       const int row = browC + ai * HALF + wr * 64 + m * 16 + fr;
;       float s = 1.f;
;       if (MODE == 1) s = scale[row];
;       for (int bj = 0; bj < 2; ++bj) {
;         uint2 o[2];
; #pragma unroll
;         for (int n = 0; n < 2; ++n) {
;           const int col = ecol + bj * HALF + wc * 32 + n * 16 + fq * 4;
;           f32x4 v = acc[ai][bj][m][n];
;           float x0, x1, x2, x3;
;           if (MODE == 2) {
;             float4 c4 = *(const float4*)(scale + col);
;             x0 = v[0] * c4.x; x1 = v[1] * c4.y; x2 = v[2] * c4.z; x3 = v[3] * c4.w;
;           } else {
;             x0 = v[0] * s; x1 = v[1] * s; x2 = v[2] * s; x3 = v[3] * s;
;           }
;           if (MODE == 1 && act) { x0 = gelu_f(x0); x1 = gelu_f(x1); x2 = gelu_f(x2); x3 = gelu_f(x3); }
;           o[n].x = pack2(x0, x1);
;           o[n].y = pack2(x2, x3);
;         }
;         auto rx = __builtin_amdgcn_permlane16_swap(o[0].x, o[1].x, false, false);
;         auto ry = __builtin_amdgcn_permlane16_swap(o[0].y, o[1].y, false, false);
;         const int colw = ecol + bj * HALF + wc * 32 + (fq & 1) * 16 + (fq >> 1) * 8;
;         *(uint4*)(C + (size_t)row * ldc + colw) = make_uint4(rx[0], ry[0], rx[1], ry[1]);
;       }
;     }
.LBB0_298:
	v_cvt_pk_bf16_f32 v70, v70, v71
	v_cvt_pk_bf16_f32 v71, v72, v73
	v_cvt_pk_bf16_f32 v72, v66, v67
	v_cvt_pk_bf16_f32 v73, v68, v69
	s_nop 0
	v_permlane16_swap_b32_e32 v70, v72
	v_permlane16_swap_b32_e32 v71, v73
	global_store_dwordx4 v[74:75], v[70:73], off offset:256
	s_and_b64 vcc, exec, s[4:5]
	v_mov_b32_e32 v66, v180
	v_pk_mul_f32 v[62:63], v[62:63], v[66:67] op_sel_hi:[1,0]
	v_pk_mul_f32 v[64:65], v[64:65], v[66:67] op_sel_hi:[1,0]
	s_cbranch_vccnz .LBB0_300
	v_pk_mul_f32 v[68:69], v[62:63], v[62:63]
	s_nop 0
	s_nop 0
	s_nop 0
	v_pk_fma_f32 v[68:69], v[68:69], v[184:185], v[186:187]
	s_nop 0
	v_pk_mul_f32 v[68:69], v[68:69], v[62:63] neg_lo:[0,1] neg_hi:[0,1]
	s_nop 0
	v_exp_f32_e32 v68, v68
	v_exp_f32_e32 v69, v69
	s_nop 0
	v_pk_add_f32 v[68:69], v[68:69], v[188:189]
	s_nop 0
	v_rcp_f32_e32 v68, v68
	v_rcp_f32_e32 v69, v69
	s_nop 0
	s_nop 0
	v_pk_mul_f32 v[62:63], v[62:63], v[68:69]
	v_pk_mul_f32 v[68:69], v[64:65], v[64:65]
	s_nop 0
	s_nop 0
	s_nop 0
	v_pk_fma_f32 v[68:69], v[68:69], v[184:185], v[186:187]
	s_nop 0
	v_pk_mul_f32 v[68:69], v[68:69], v[64:65] neg_lo:[0,1] neg_hi:[0,1]
	s_nop 0
	v_exp_f32_e32 v68, v68
	v_exp_f32_e32 v69, v69
	s_nop 0
	v_pk_add_f32 v[68:69], v[68:69], v[188:189]
	s_nop 0
	v_rcp_f32_e32 v68, v68
	v_rcp_f32_e32 v69, v69
	s_nop 0
	s_nop 0
	v_pk_mul_f32 v[64:65], v[64:65], v[68:69]
.LBB0_300:
	v_mov_b32_e32 v67, v66
	v_pk_mul_f32 v[58:59], v[58:59], v[66:67]
	s_and_b64 vcc, exec, s[4:5]
	v_pk_mul_f32 v[60:61], v[60:61], v[66:67]
	s_cbranch_vccnz .LBB0_302
	v_pk_mul_f32 v[68:69], v[58:59], v[58:59]
	s_nop 0
	s_nop 0
	s_nop 0
	v_pk_fma_f32 v[68:69], v[68:69], v[184:185], v[186:187]
	s_nop 0
	v_pk_mul_f32 v[68:69], v[68:69], v[58:59] neg_lo:[0,1] neg_hi:[0,1]
	s_nop 0
	v_exp_f32_e32 v68, v68
	v_exp_f32_e32 v69, v69
	s_nop 0
	v_pk_add_f32 v[68:69], v[68:69], v[188:189]
	s_nop 0
	v_rcp_f32_e32 v68, v68
	v_rcp_f32_e32 v69, v69
	s_nop 0
	s_nop 0
	v_pk_mul_f32 v[58:59], v[58:59], v[68:69]
	v_pk_mul_f32 v[68:69], v[60:61], v[60:61]
	s_nop 0
	s_nop 0
	s_nop 0
	v_pk_fma_f32 v[68:69], v[68:69], v[184:185], v[186:187]
	s_nop 0
	v_pk_mul_f32 v[68:69], v[68:69], v[60:61] neg_lo:[0,1] neg_hi:[0,1]
	s_nop 0
	v_exp_f32_e32 v68, v68
	v_exp_f32_e32 v69, v69
	s_nop 0
	v_pk_add_f32 v[68:69], v[68:69], v[188:189]
	s_nop 0
	v_rcp_f32_e32 v68, v68
	v_rcp_f32_e32 v69, v69
	s_nop 0
	s_nop 0
	v_pk_mul_f32 v[60:61], v[60:61], v[68:69]
.LBB0_302:
	v_add_u32_e32 v0, 0x80, v130
	v_cvt_pk_bf16_f32 v62, v62, v63
	v_cvt_pk_bf16_f32 v63, v64, v65
	v_mad_u64_u32 v[64:65], s[10:11], v0, s22, 0
	v_ashrrev_i32_e32 v68, 31, v0
	v_mov_b32_e32 v0, v65
	v_mad_u64_u32 v[68:69], s[10:11], v68, s22, v[0:1]
	v_mov_b32_e32 v65, v68
	v_lshl_add_u64 v[68:69], v[64:65], 1, s[6:7]
	v_cvt_pk_bf16_f32 v64, v58, v59
	v_cvt_pk_bf16_f32 v65, v60, v61
	s_nop 0
	v_permlane16_swap_b32_e32 v62, v64
	v_permlane16_swap_b32_e32 v63, v65
	v_lshl_add_u64 v[58:59], v[122:123], 1, v[68:69]
	v_pk_mul_f32 v[54:55], v[54:55], v[66:67]
	s_and_b64 vcc, exec, s[4:5]
	v_pk_mul_f32 v[56:57], v[56:57], v[66:67]
	global_store_dwordx4 v[58:59], v[62:65], off
	s_cbranch_vccnz .LBB0_304
	v_pk_mul_f32 v[60:61], v[54:55], v[54:55]
	s_nop 0
	s_nop 0
	s_nop 0
	v_pk_fma_f32 v[60:61], v[60:61], v[184:185], v[186:187]
	s_nop 0
	v_pk_mul_f32 v[60:61], v[60:61], v[54:55] neg_lo:[0,1] neg_hi:[0,1]
	s_nop 0
	v_exp_f32_e32 v60, v60
	v_exp_f32_e32 v61, v61
	s_nop 0
	v_pk_add_f32 v[60:61], v[60:61], v[188:189]
	s_nop 0
	v_rcp_f32_e32 v60, v60
	v_rcp_f32_e32 v61, v61
	s_nop 0
	s_nop 0
	v_pk_mul_f32 v[54:55], v[54:55], v[60:61]
	v_pk_mul_f32 v[60:61], v[56:57], v[56:57]
	s_nop 0
	s_nop 0
	s_nop 0
	v_pk_fma_f32 v[60:61], v[60:61], v[184:185], v[186:187]
	s_nop 0
	v_pk_mul_f32 v[60:61], v[60:61], v[56:57] neg_lo:[0,1] neg_hi:[0,1]
	s_nop 0
	v_exp_f32_e32 v60, v60
	v_exp_f32_e32 v61, v61
	s_nop 0
	v_pk_add_f32 v[60:61], v[60:61], v[188:189]
	s_nop 0
	v_rcp_f32_e32 v60, v60
	v_rcp_f32_e32 v61, v61
	s_nop 0
	s_nop 0
	v_pk_mul_f32 v[56:57], v[56:57], v[60:61]
.LBB0_304:
	v_pk_mul_f32 v[50:51], v[50:51], v[66:67]
	s_and_b64 vcc, exec, s[4:5]
	v_pk_mul_f32 v[52:53], v[52:53], v[66:67]
	s_cbranch_vccnz .LBB0_306
	v_pk_mul_f32 v[60:61], v[50:51], v[50:51]
	s_nop 0
	s_nop 0
	s_nop 0
	v_pk_fma_f32 v[60:61], v[60:61], v[184:185], v[186:187]
	s_nop 0
	v_pk_mul_f32 v[60:61], v[60:61], v[50:51] neg_lo:[0,1] neg_hi:[0,1]
	s_nop 0
	v_exp_f32_e32 v60, v60
	v_exp_f32_e32 v61, v61
	s_nop 0
	v_pk_add_f32 v[60:61], v[60:61], v[188:189]
	s_nop 0
	v_rcp_f32_e32 v60, v60
	v_rcp_f32_e32 v61, v61
	s_nop 0
	s_nop 0
	v_pk_mul_f32 v[50:51], v[50:51], v[60:61]
	v_pk_mul_f32 v[60:61], v[52:53], v[52:53]
	s_nop 0
	s_nop 0
	s_nop 0
	v_pk_fma_f32 v[60:61], v[60:61], v[184:185], v[186:187]
	s_nop 0
	v_pk_mul_f32 v[60:61], v[60:61], v[52:53] neg_lo:[0,1] neg_hi:[0,1]
	s_nop 0
	v_exp_f32_e32 v60, v60
	v_exp_f32_e32 v61, v61
	s_nop 0
	v_pk_add_f32 v[60:61], v[60:61], v[188:189]
	s_nop 0
	v_rcp_f32_e32 v60, v60
	v_rcp_f32_e32 v61, v61
	s_nop 0
	s_nop 0
	v_pk_mul_f32 v[52:53], v[52:53], v[60:61]
; __device__ __forceinline__ float gelu_f(float x) {
;   const float c2 = 2.f * 0.7978845608028654f * 1.4426950408889634f;
;   float p = __builtin_fmaf(x * x, 0.044715f * c2, c2);
;   float e = __builtin_amdgcn_exp2f(-x * p);
;   return x * __builtin_amdgcn_rcpf(1.f + e);
; }
; template <int MODE>
; __device__ __forceinline__ void gemm_tile(const int ph, const int which, const int pm, const int pn) {
;     ...
;   for (int ai = 0; ai < 2; ++ai)
;     for (int m = 0; m < 4; ++m) {
;       const int row = browC + ai * HALF + wr * 64 + m * 16 + fr;
;       float s = 1.f;
;       if (MODE == 1) s = scale[row];
;       for (int bj = 0; bj < 2; ++bj) {
;         uint2 o[2];
; #pragma unroll
;         for (int n = 0; n < 2; ++n) {
;           const int col = ecol + bj * HALF + wc * 32 + n * 16 + fq * 4;
;           f32x4 v = acc[ai][bj][m][n];
;           float x0, x1, x2, x3;
;           if (MODE == 2) {
;             float4 c4 = *(const float4*)(scale + col);
;             x0 = v[0] * c4.x; x1 = v[1] * c4.y; x2 = v[2] * c4.z; x3 = v[3] * c4.w;
;           } else {
;             x0 = v[0] * s; x1 = v[1] * s; x2 = v[2] * s; x3 = v[3] * s;
;           }
;           if (MODE == 1 && act) { x0 = gelu_f(x0); x1 = gelu_f(x1); x2 = gelu_f(x2); x3 = gelu_f(x3); }
;           o[n].x = pack2(x0, x1);
;           o[n].y = pack2(x2, x3);
;         }
;         auto rx = __builtin_amdgcn_permlane16_swap(o[0].x, o[1].x, false, false);
;         auto ry = __builtin_amdgcn_permlane16_swap(o[0].y, o[1].y, false, false);
;         const int colw = ecol + bj * HALF + wc * 32 + (fq & 1) * 16 + (fq >> 1) * 8;
;         *(uint4*)(C + (size_t)row * ldc + colw) = make_uint4(rx[0], ry[0], rx[1], ry[1]);
;       }
;     }
.LBB0_306:
	v_cvt_pk_bf16_f32 v54, v54, v55
	v_cvt_pk_bf16_f32 v55, v56, v57
	v_cvt_pk_bf16_f32 v56, v50, v51
	v_cvt_pk_bf16_f32 v57, v52, v53
	s_nop 0
	v_permlane16_swap_b32_e32 v54, v56
	v_permlane16_swap_b32_e32 v55, v57
	global_store_dwordx4 v[58:59], v[54:57], off offset:256
	s_and_b64 vcc, exec, s[4:5]
	v_mov_b32_e32 v50, v181
	v_pk_mul_f32 v[46:47], v[46:47], v[50:51] op_sel_hi:[1,0]
	v_pk_mul_f32 v[48:49], v[48:49], v[50:51] op_sel_hi:[1,0]
	s_cbranch_vccnz .LBB0_308
	v_pk_mul_f32 v[52:53], v[46:47], v[46:47]
	s_nop 0
	s_nop 0
	s_nop 0
	v_pk_fma_f32 v[52:53], v[52:53], v[184:185], v[186:187]
	s_nop 0
	v_pk_mul_f32 v[52:53], v[52:53], v[46:47] neg_lo:[0,1] neg_hi:[0,1]
	s_nop 0
	v_exp_f32_e32 v52, v52
	v_exp_f32_e32 v53, v53
	s_nop 0
	v_pk_add_f32 v[52:53], v[52:53], v[188:189]
	s_nop 0
	v_rcp_f32_e32 v52, v52
	v_rcp_f32_e32 v53, v53
	s_nop 0
	s_nop 0
	v_pk_mul_f32 v[46:47], v[46:47], v[52:53]
	v_pk_mul_f32 v[52:53], v[48:49], v[48:49]
	s_nop 0
	s_nop 0
	s_nop 0
	v_pk_fma_f32 v[52:53], v[52:53], v[184:185], v[186:187]
	s_nop 0
	v_pk_mul_f32 v[52:53], v[52:53], v[48:49] neg_lo:[0,1] neg_hi:[0,1]
	s_nop 0
	v_exp_f32_e32 v52, v52
	v_exp_f32_e32 v53, v53
	s_nop 0
	v_pk_add_f32 v[52:53], v[52:53], v[188:189]
	s_nop 0
	v_rcp_f32_e32 v52, v52
	v_rcp_f32_e32 v53, v53
	s_nop 0
	s_nop 0
	v_pk_mul_f32 v[48:49], v[48:49], v[52:53]
.LBB0_308:
	v_mov_b32_e32 v51, v50
	v_pk_mul_f32 v[42:43], v[42:43], v[50:51]
	s_and_b64 vcc, exec, s[4:5]
	v_pk_mul_f32 v[44:45], v[44:45], v[50:51]
	s_cbranch_vccnz .LBB0_310
	v_pk_mul_f32 v[52:53], v[42:43], v[42:43]
	s_nop 0
	s_nop 0
	s_nop 0
	v_pk_fma_f32 v[52:53], v[52:53], v[184:185], v[186:187]
	s_nop 0
	v_pk_mul_f32 v[52:53], v[52:53], v[42:43] neg_lo:[0,1] neg_hi:[0,1]
	s_nop 0
	v_exp_f32_e32 v52, v52
	v_exp_f32_e32 v53, v53
	s_nop 0
	v_pk_add_f32 v[52:53], v[52:53], v[188:189]
	s_nop 0
	v_rcp_f32_e32 v52, v52
	v_rcp_f32_e32 v53, v53
	s_nop 0
	s_nop 0
	v_pk_mul_f32 v[42:43], v[42:43], v[52:53]
	v_pk_mul_f32 v[52:53], v[44:45], v[44:45]
	s_nop 0
	s_nop 0
	s_nop 0
	v_pk_fma_f32 v[52:53], v[52:53], v[184:185], v[186:187]
	s_nop 0
	v_pk_mul_f32 v[52:53], v[52:53], v[44:45] neg_lo:[0,1] neg_hi:[0,1]
	s_nop 0
	v_exp_f32_e32 v52, v52
	v_exp_f32_e32 v53, v53
	s_nop 0
	v_pk_add_f32 v[52:53], v[52:53], v[188:189]
	s_nop 0
	v_rcp_f32_e32 v52, v52
	v_rcp_f32_e32 v53, v53
	s_nop 0
	s_nop 0
	v_pk_mul_f32 v[44:45], v[44:45], v[52:53]
.LBB0_310:
	v_add_u32_e32 v0, 0x90, v130
	v_cvt_pk_bf16_f32 v46, v46, v47
	v_cvt_pk_bf16_f32 v47, v48, v49
	v_mad_u64_u32 v[48:49], s[10:11], v0, s22, 0
	v_ashrrev_i32_e32 v52, 31, v0
	v_mov_b32_e32 v0, v49
	v_mad_u64_u32 v[52:53], s[10:11], v52, s22, v[0:1]
	v_mov_b32_e32 v49, v52
	v_lshl_add_u64 v[52:53], v[48:49], 1, s[6:7]
	v_cvt_pk_bf16_f32 v48, v42, v43
	v_cvt_pk_bf16_f32 v49, v44, v45
	s_nop 0
	v_permlane16_swap_b32_e32 v46, v48
	v_permlane16_swap_b32_e32 v47, v49
	v_lshl_add_u64 v[42:43], v[122:123], 1, v[52:53]
	v_pk_mul_f32 v[38:39], v[38:39], v[50:51]
	s_and_b64 vcc, exec, s[4:5]
	v_pk_mul_f32 v[40:41], v[40:41], v[50:51]
	global_store_dwordx4 v[42:43], v[46:49], off
	s_cbranch_vccnz .LBB0_312
	v_pk_mul_f32 v[44:45], v[38:39], v[38:39]
	s_nop 0
	s_nop 0
	s_nop 0
	v_pk_fma_f32 v[44:45], v[44:45], v[184:185], v[186:187]
	s_nop 0
	v_pk_mul_f32 v[44:45], v[44:45], v[38:39] neg_lo:[0,1] neg_hi:[0,1]
	s_nop 0
	v_exp_f32_e32 v44, v44
	v_exp_f32_e32 v45, v45
	s_nop 0
	v_pk_add_f32 v[44:45], v[44:45], v[188:189]
	s_nop 0
	v_rcp_f32_e32 v44, v44
	v_rcp_f32_e32 v45, v45
	s_nop 0
	s_nop 0
	v_pk_mul_f32 v[38:39], v[38:39], v[44:45]
	v_pk_mul_f32 v[44:45], v[40:41], v[40:41]
	s_nop 0
	s_nop 0
	s_nop 0
	v_pk_fma_f32 v[44:45], v[44:45], v[184:185], v[186:187]
	s_nop 0
	v_pk_mul_f32 v[44:45], v[44:45], v[40:41] neg_lo:[0,1] neg_hi:[0,1]
	s_nop 0
	v_exp_f32_e32 v44, v44
	v_exp_f32_e32 v45, v45
	s_nop 0
	v_pk_add_f32 v[44:45], v[44:45], v[188:189]
	s_nop 0
	v_rcp_f32_e32 v44, v44
	v_rcp_f32_e32 v45, v45
	s_nop 0
	s_nop 0
	v_pk_mul_f32 v[40:41], v[40:41], v[44:45]
.LBB0_312:
	v_pk_mul_f32 v[34:35], v[34:35], v[50:51]
	s_and_b64 vcc, exec, s[4:5]
	v_pk_mul_f32 v[36:37], v[36:37], v[50:51]
	s_cbranch_vccnz .LBB0_314
	v_pk_mul_f32 v[44:45], v[34:35], v[34:35]
	s_nop 0
	s_nop 0
	s_nop 0
	v_pk_fma_f32 v[44:45], v[44:45], v[184:185], v[186:187]
	s_nop 0
	v_pk_mul_f32 v[44:45], v[44:45], v[34:35] neg_lo:[0,1] neg_hi:[0,1]
	s_nop 0
	v_exp_f32_e32 v44, v44
	v_exp_f32_e32 v45, v45
	s_nop 0
	v_pk_add_f32 v[44:45], v[44:45], v[188:189]
	s_nop 0
	v_rcp_f32_e32 v44, v44
	v_rcp_f32_e32 v45, v45
	s_nop 0
	s_nop 0
	v_pk_mul_f32 v[34:35], v[34:35], v[44:45]
	v_pk_mul_f32 v[44:45], v[36:37], v[36:37]
	s_nop 0
	s_nop 0
	s_nop 0
	v_pk_fma_f32 v[44:45], v[44:45], v[184:185], v[186:187]
	s_nop 0
	v_pk_mul_f32 v[44:45], v[44:45], v[36:37] neg_lo:[0,1] neg_hi:[0,1]
	s_nop 0
	v_exp_f32_e32 v44, v44
	v_exp_f32_e32 v45, v45
	s_nop 0
	v_pk_add_f32 v[44:45], v[44:45], v[188:189]
	s_nop 0
	v_rcp_f32_e32 v44, v44
	v_rcp_f32_e32 v45, v45
	s_nop 0
	s_nop 0
	v_pk_mul_f32 v[36:37], v[36:37], v[44:45]
; __device__ __forceinline__ float gelu_f(float x) {
;   const float c2 = 2.f * 0.7978845608028654f * 1.4426950408889634f;
;   float p = __builtin_fmaf(x * x, 0.044715f * c2, c2);
;   float e = __builtin_amdgcn_exp2f(-x * p);
;   return x * __builtin_amdgcn_rcpf(1.f + e);
; }
; template <int MODE>
; __device__ __forceinline__ void gemm_tile(const int ph, const int which, const int pm, const int pn) {
;     ...
;   for (int ai = 0; ai < 2; ++ai)
;     for (int m = 0; m < 4; ++m) {
;       const int row = browC + ai * HALF + wr * 64 + m * 16 + fr;
;       float s = 1.f;
;       if (MODE == 1) s = scale[row];
;       for (int bj = 0; bj < 2; ++bj) {
;         uint2 o[2];
; #pragma unroll
;         for (int n = 0; n < 2; ++n) {
;           const int col = ecol + bj * HALF + wc * 32 + n * 16 + fq * 4;
;           f32x4 v = acc[ai][bj][m][n];
;           float x0, x1, x2, x3;
;           if (MODE == 2) {
;             float4 c4 = *(const float4*)(scale + col);
;             x0 = v[0] * c4.x; x1 = v[1] * c4.y; x2 = v[2] * c4.z; x3 = v[3] * c4.w;
;           } else {
;             x0 = v[0] * s; x1 = v[1] * s; x2 = v[2] * s; x3 = v[3] * s;
;           }
;           if (MODE == 1 && act) { x0 = gelu_f(x0); x1 = gelu_f(x1); x2 = gelu_f(x2); x3 = gelu_f(x3); }
;           o[n].x = pack2(x0, x1);
;           o[n].y = pack2(x2, x3);
;         }
;         auto rx = __builtin_amdgcn_permlane16_swap(o[0].x, o[1].x, false, false);
;         auto ry = __builtin_amdgcn_permlane16_swap(o[0].y, o[1].y, false, false);
;         const int colw = ecol + bj * HALF + wc * 32 + (fq & 1) * 16 + (fq >> 1) * 8;
;         *(uint4*)(C + (size_t)row * ldc + colw) = make_uint4(rx[0], ry[0], rx[1], ry[1]);
;       }
;     }
.LBB0_314:
	v_cvt_pk_bf16_f32 v38, v38, v39
	v_cvt_pk_bf16_f32 v39, v40, v41
	v_cvt_pk_bf16_f32 v40, v34, v35
	v_cvt_pk_bf16_f32 v41, v36, v37
	s_nop 0
	v_permlane16_swap_b32_e32 v38, v40
	v_permlane16_swap_b32_e32 v39, v41
	global_store_dwordx4 v[42:43], v[38:41], off offset:256
	s_and_b64 vcc, exec, s[4:5]
	v_mov_b32_e32 v34, v182
	v_pk_mul_f32 v[30:31], v[30:31], v[34:35] op_sel_hi:[1,0]
	v_pk_mul_f32 v[32:33], v[32:33], v[34:35] op_sel_hi:[1,0]
	s_cbranch_vccnz .LBB0_316
	v_pk_mul_f32 v[36:37], v[30:31], v[30:31]
	s_nop 0
	s_nop 0
	s_nop 0
	v_pk_fma_f32 v[36:37], v[36:37], v[184:185], v[186:187]
	s_nop 0
	v_pk_mul_f32 v[36:37], v[36:37], v[30:31] neg_lo:[0,1] neg_hi:[0,1]
	s_nop 0
	v_exp_f32_e32 v36, v36
	v_exp_f32_e32 v37, v37
	s_nop 0
	v_pk_add_f32 v[36:37], v[36:37], v[188:189]
	s_nop 0
	v_rcp_f32_e32 v36, v36
	v_rcp_f32_e32 v37, v37
	s_nop 0
	s_nop 0
	v_pk_mul_f32 v[30:31], v[30:31], v[36:37]
	v_pk_mul_f32 v[36:37], v[32:33], v[32:33]
	s_nop 0
	s_nop 0
	s_nop 0
	v_pk_fma_f32 v[36:37], v[36:37], v[184:185], v[186:187]
	s_nop 0
	v_pk_mul_f32 v[36:37], v[36:37], v[32:33] neg_lo:[0,1] neg_hi:[0,1]
	s_nop 0
	v_exp_f32_e32 v36, v36
	v_exp_f32_e32 v37, v37
	s_nop 0
	v_pk_add_f32 v[36:37], v[36:37], v[188:189]
	s_nop 0
	v_rcp_f32_e32 v36, v36
	v_rcp_f32_e32 v37, v37
	s_nop 0
	s_nop 0
	v_pk_mul_f32 v[32:33], v[32:33], v[36:37]
.LBB0_316:
	v_mov_b32_e32 v35, v34
	v_pk_mul_f32 v[26:27], v[26:27], v[34:35]
	s_and_b64 vcc, exec, s[4:5]
	v_pk_mul_f32 v[28:29], v[28:29], v[34:35]
	s_cbranch_vccnz .LBB0_318
	v_pk_mul_f32 v[36:37], v[26:27], v[26:27]
	s_nop 0
	s_nop 0
	s_nop 0
	v_pk_fma_f32 v[36:37], v[36:37], v[184:185], v[186:187]
	s_nop 0
	v_pk_mul_f32 v[36:37], v[36:37], v[26:27] neg_lo:[0,1] neg_hi:[0,1]
	s_nop 0
	v_exp_f32_e32 v36, v36
	v_exp_f32_e32 v37, v37
	s_nop 0
	v_pk_add_f32 v[36:37], v[36:37], v[188:189]
	s_nop 0
	v_rcp_f32_e32 v36, v36
	v_rcp_f32_e32 v37, v37
	s_nop 0
	s_nop 0
	v_pk_mul_f32 v[26:27], v[26:27], v[36:37]
	v_pk_mul_f32 v[36:37], v[28:29], v[28:29]
	s_nop 0
	s_nop 0
	s_nop 0
	v_pk_fma_f32 v[36:37], v[36:37], v[184:185], v[186:187]
	s_nop 0
	v_pk_mul_f32 v[36:37], v[36:37], v[28:29] neg_lo:[0,1] neg_hi:[0,1]
	s_nop 0
	v_exp_f32_e32 v36, v36
	v_exp_f32_e32 v37, v37
	s_nop 0
	v_pk_add_f32 v[36:37], v[36:37], v[188:189]
	s_nop 0
	v_rcp_f32_e32 v36, v36
	v_rcp_f32_e32 v37, v37
	s_nop 0
	s_nop 0
	v_pk_mul_f32 v[28:29], v[28:29], v[36:37]
.LBB0_318:
	v_add_u32_e32 v0, 0xa0, v130
	v_cvt_pk_bf16_f32 v30, v30, v31
	v_cvt_pk_bf16_f32 v31, v32, v33
	v_mad_u64_u32 v[32:33], s[10:11], v0, s22, 0
	v_ashrrev_i32_e32 v36, 31, v0
	v_mov_b32_e32 v0, v33
	v_mad_u64_u32 v[36:37], s[10:11], v36, s22, v[0:1]
	v_mov_b32_e32 v33, v36
	v_lshl_add_u64 v[36:37], v[32:33], 1, s[6:7]
	v_cvt_pk_bf16_f32 v32, v26, v27
	v_cvt_pk_bf16_f32 v33, v28, v29
	s_nop 0
	v_permlane16_swap_b32_e32 v30, v32
	v_permlane16_swap_b32_e32 v31, v33
	v_lshl_add_u64 v[26:27], v[122:123], 1, v[36:37]
	v_pk_mul_f32 v[22:23], v[22:23], v[34:35]
	s_and_b64 vcc, exec, s[4:5]
	v_pk_mul_f32 v[24:25], v[24:25], v[34:35]
	global_store_dwordx4 v[26:27], v[30:33], off
	s_cbranch_vccnz .LBB0_320
	v_pk_mul_f32 v[28:29], v[22:23], v[22:23]
	s_nop 0
	s_nop 0
	s_nop 0
	v_pk_fma_f32 v[28:29], v[28:29], v[184:185], v[186:187]
	s_nop 0
	v_pk_mul_f32 v[28:29], v[28:29], v[22:23] neg_lo:[0,1] neg_hi:[0,1]
	s_nop 0
	v_exp_f32_e32 v28, v28
	v_exp_f32_e32 v29, v29
	s_nop 0
	v_pk_add_f32 v[28:29], v[28:29], v[188:189]
	s_nop 0
	v_rcp_f32_e32 v28, v28
	v_rcp_f32_e32 v29, v29
	s_nop 0
	s_nop 0
	v_pk_mul_f32 v[22:23], v[22:23], v[28:29]
	v_pk_mul_f32 v[28:29], v[24:25], v[24:25]
	s_nop 0
	s_nop 0
	s_nop 0
	v_pk_fma_f32 v[28:29], v[28:29], v[184:185], v[186:187]
	s_nop 0
	v_pk_mul_f32 v[28:29], v[28:29], v[24:25] neg_lo:[0,1] neg_hi:[0,1]
	s_nop 0
	v_exp_f32_e32 v28, v28
	v_exp_f32_e32 v29, v29
	s_nop 0
	v_pk_add_f32 v[28:29], v[28:29], v[188:189]
	s_nop 0
	v_rcp_f32_e32 v28, v28
	v_rcp_f32_e32 v29, v29
	s_nop 0
	s_nop 0
	v_pk_mul_f32 v[24:25], v[24:25], v[28:29]
.LBB0_320:
	v_pk_mul_f32 v[18:19], v[18:19], v[34:35]
	s_and_b64 vcc, exec, s[4:5]
	v_pk_mul_f32 v[20:21], v[20:21], v[34:35]
	s_cbranch_vccnz .LBB0_322
	v_pk_mul_f32 v[28:29], v[18:19], v[18:19]
	s_nop 0
	s_nop 0
	s_nop 0
	v_pk_fma_f32 v[28:29], v[28:29], v[184:185], v[186:187]
	s_nop 0
	v_pk_mul_f32 v[28:29], v[28:29], v[18:19] neg_lo:[0,1] neg_hi:[0,1]
	s_nop 0
	v_exp_f32_e32 v28, v28
	v_exp_f32_e32 v29, v29
	s_nop 0
	v_pk_add_f32 v[28:29], v[28:29], v[188:189]
	s_nop 0
	v_rcp_f32_e32 v28, v28
	v_rcp_f32_e32 v29, v29
	s_nop 0
	s_nop 0
	v_pk_mul_f32 v[18:19], v[18:19], v[28:29]
	v_pk_mul_f32 v[28:29], v[20:21], v[20:21]
	s_nop 0
	s_nop 0
	s_nop 0
	v_pk_fma_f32 v[28:29], v[28:29], v[184:185], v[186:187]
	s_nop 0
	v_pk_mul_f32 v[28:29], v[28:29], v[20:21] neg_lo:[0,1] neg_hi:[0,1]
	s_nop 0
	v_exp_f32_e32 v28, v28
	v_exp_f32_e32 v29, v29
	s_nop 0
	v_pk_add_f32 v[28:29], v[28:29], v[188:189]
	s_nop 0
	v_rcp_f32_e32 v28, v28
	v_rcp_f32_e32 v29, v29
	s_nop 0
	s_nop 0
	v_pk_mul_f32 v[20:21], v[20:21], v[28:29]
; __device__ __forceinline__ float gelu_f(float x) {
;   const float c2 = 2.f * 0.7978845608028654f * 1.4426950408889634f;
;   float p = __builtin_fmaf(x * x, 0.044715f * c2, c2);
;   float e = __builtin_amdgcn_exp2f(-x * p);
;   return x * __builtin_amdgcn_rcpf(1.f + e);
; }
; template <int MODE>
; __device__ __forceinline__ void gemm_tile(const int ph, const int which, const int pm, const int pn) {
;     ...
;   for (int ai = 0; ai < 2; ++ai)
;     for (int m = 0; m < 4; ++m) {
;       const int row = browC + ai * HALF + wr * 64 + m * 16 + fr;
;       float s = 1.f;
;       if (MODE == 1) s = scale[row];
;       for (int bj = 0; bj < 2; ++bj) {
;         uint2 o[2];
; #pragma unroll
;         for (int n = 0; n < 2; ++n) {
;           const int col = ecol + bj * HALF + wc * 32 + n * 16 + fq * 4;
;           f32x4 v = acc[ai][bj][m][n];
;           float x0, x1, x2, x3;
;           if (MODE == 2) {
;             float4 c4 = *(const float4*)(scale + col);
;             x0 = v[0] * c4.x; x1 = v[1] * c4.y; x2 = v[2] * c4.z; x3 = v[3] * c4.w;
;           } else {
;             x0 = v[0] * s; x1 = v[1] * s; x2 = v[2] * s; x3 = v[3] * s;
;           }
;           if (MODE == 1 && act) { x0 = gelu_f(x0); x1 = gelu_f(x1); x2 = gelu_f(x2); x3 = gelu_f(x3); }
;           o[n].x = pack2(x0, x1);
;           o[n].y = pack2(x2, x3);
;         }
;         auto rx = __builtin_amdgcn_permlane16_swap(o[0].x, o[1].x, false, false);
;         auto ry = __builtin_amdgcn_permlane16_swap(o[0].y, o[1].y, false, false);
;         const int colw = ecol + bj * HALF + wc * 32 + (fq & 1) * 16 + (fq >> 1) * 8;
;         *(uint4*)(C + (size_t)row * ldc + colw) = make_uint4(rx[0], ry[0], rx[1], ry[1]);
;       }
;     }
.LBB0_322:
	v_cvt_pk_bf16_f32 v22, v22, v23
	v_cvt_pk_bf16_f32 v23, v24, v25
	v_cvt_pk_bf16_f32 v24, v18, v19
	v_cvt_pk_bf16_f32 v25, v20, v21
	s_nop 0
	v_permlane16_swap_b32_e32 v22, v24
	v_permlane16_swap_b32_e32 v23, v25
	global_store_dwordx4 v[26:27], v[22:25], off offset:256
	s_and_b64 vcc, exec, s[4:5]
	v_mov_b32_e32 v18, v183
	v_pk_mul_f32 v[14:15], v[14:15], v[18:19] op_sel_hi:[1,0]
	v_pk_mul_f32 v[16:17], v[16:17], v[18:19] op_sel_hi:[1,0]
	s_cbranch_vccnz .LBB0_324
	v_pk_mul_f32 v[20:21], v[14:15], v[14:15]
	s_nop 0
	s_nop 0
	s_nop 0
	v_pk_fma_f32 v[20:21], v[20:21], v[184:185], v[186:187]
	s_nop 0
	v_pk_mul_f32 v[20:21], v[20:21], v[14:15] neg_lo:[0,1] neg_hi:[0,1]
	s_nop 0
	v_exp_f32_e32 v20, v20
	v_exp_f32_e32 v21, v21
	s_nop 0
	v_pk_add_f32 v[20:21], v[20:21], v[188:189]
	s_nop 0
	v_rcp_f32_e32 v20, v20
	v_rcp_f32_e32 v21, v21
	s_nop 0
	s_nop 0
	v_pk_mul_f32 v[14:15], v[14:15], v[20:21]
	v_pk_mul_f32 v[20:21], v[16:17], v[16:17]
	s_nop 0
	s_nop 0
	s_nop 0
	v_pk_fma_f32 v[20:21], v[20:21], v[184:185], v[186:187]
	s_nop 0
	v_pk_mul_f32 v[20:21], v[20:21], v[16:17] neg_lo:[0,1] neg_hi:[0,1]
	s_nop 0
	v_exp_f32_e32 v20, v20
	v_exp_f32_e32 v21, v21
	s_nop 0
	v_pk_add_f32 v[20:21], v[20:21], v[188:189]
	s_nop 0
	v_rcp_f32_e32 v20, v20
	v_rcp_f32_e32 v21, v21
	s_nop 0
	s_nop 0
	v_pk_mul_f32 v[16:17], v[16:17], v[20:21]
.LBB0_324:
	v_mov_b32_e32 v19, v18
	v_pk_mul_f32 v[10:11], v[10:11], v[18:19]
	s_and_b64 vcc, exec, s[4:5]
	v_pk_mul_f32 v[12:13], v[12:13], v[18:19]
	s_cbranch_vccnz .LBB0_326
	v_pk_mul_f32 v[20:21], v[10:11], v[10:11]
	s_nop 0
	s_nop 0
	s_nop 0
	v_pk_fma_f32 v[20:21], v[20:21], v[184:185], v[186:187]
	s_nop 0
	v_pk_mul_f32 v[20:21], v[20:21], v[10:11] neg_lo:[0,1] neg_hi:[0,1]
	s_nop 0
	v_exp_f32_e32 v20, v20
	v_exp_f32_e32 v21, v21
	s_nop 0
	v_pk_add_f32 v[20:21], v[20:21], v[188:189]
	s_nop 0
	v_rcp_f32_e32 v20, v20
	v_rcp_f32_e32 v21, v21
	s_nop 0
	s_nop 0
	v_pk_mul_f32 v[10:11], v[10:11], v[20:21]
	v_pk_mul_f32 v[20:21], v[12:13], v[12:13]
	s_nop 0
	s_nop 0
	s_nop 0
	v_pk_fma_f32 v[20:21], v[20:21], v[184:185], v[186:187]
	s_nop 0
	v_pk_mul_f32 v[20:21], v[20:21], v[12:13] neg_lo:[0,1] neg_hi:[0,1]
	s_nop 0
	v_exp_f32_e32 v20, v20
	v_exp_f32_e32 v21, v21
	s_nop 0
	v_pk_add_f32 v[20:21], v[20:21], v[188:189]
	s_nop 0
	v_rcp_f32_e32 v20, v20
	v_rcp_f32_e32 v21, v21
	s_nop 0
	s_nop 0
	v_pk_mul_f32 v[12:13], v[12:13], v[20:21]
.LBB0_326:
	v_add_u32_e32 v0, 0xb0, v130
	v_cvt_pk_bf16_f32 v14, v14, v15
	v_cvt_pk_bf16_f32 v15, v16, v17
	v_mad_u64_u32 v[16:17], s[10:11], v0, s22, 0
	v_ashrrev_i32_e32 v20, 31, v0
	v_mov_b32_e32 v0, v17
	v_mad_u64_u32 v[20:21], s[10:11], v20, s22, v[0:1]
	v_mov_b32_e32 v17, v20
	v_lshl_add_u64 v[20:21], v[16:17], 1, s[6:7]
	v_cvt_pk_bf16_f32 v16, v10, v11
	v_cvt_pk_bf16_f32 v17, v12, v13
	s_nop 0
	v_permlane16_swap_b32_e32 v14, v16
	v_permlane16_swap_b32_e32 v15, v17
	v_lshl_add_u64 v[10:11], v[122:123], 1, v[20:21]
	v_pk_mul_f32 v[6:7], v[6:7], v[18:19]
	s_and_b64 vcc, exec, s[4:5]
	v_pk_mul_f32 v[8:9], v[8:9], v[18:19]
	global_store_dwordx4 v[10:11], v[14:17], off
	s_cbranch_vccnz .LBB0_328
	v_pk_mul_f32 v[12:13], v[6:7], v[6:7]
	s_nop 0
	s_nop 0
	s_nop 0
	v_pk_fma_f32 v[12:13], v[12:13], v[184:185], v[186:187]
	s_nop 0
	v_pk_mul_f32 v[12:13], v[12:13], v[6:7] neg_lo:[0,1] neg_hi:[0,1]
	s_nop 0
	v_exp_f32_e32 v12, v12
	v_exp_f32_e32 v13, v13
	s_nop 0
	v_pk_add_f32 v[12:13], v[12:13], v[188:189]
	s_nop 0
	v_rcp_f32_e32 v12, v12
	v_rcp_f32_e32 v13, v13
	s_nop 0
	s_nop 0
	v_pk_mul_f32 v[6:7], v[6:7], v[12:13]
	v_pk_mul_f32 v[12:13], v[8:9], v[8:9]
	s_nop 0
	s_nop 0
	s_nop 0
	v_pk_fma_f32 v[12:13], v[12:13], v[184:185], v[186:187]
	s_nop 0
	v_pk_mul_f32 v[12:13], v[12:13], v[8:9] neg_lo:[0,1] neg_hi:[0,1]
	s_nop 0
	v_exp_f32_e32 v12, v12
	v_exp_f32_e32 v13, v13
	s_nop 0
	v_pk_add_f32 v[12:13], v[12:13], v[188:189]
	s_nop 0
	v_rcp_f32_e32 v12, v12
	v_rcp_f32_e32 v13, v13
	s_nop 0
	s_nop 0
	v_pk_mul_f32 v[8:9], v[8:9], v[12:13]
.LBB0_328:
	v_pk_mul_f32 v[2:3], v[2:3], v[18:19]
	s_and_b64 vcc, exec, s[4:5]
	v_pk_mul_f32 v[4:5], v[4:5], v[18:19]
	s_cbranch_vccnz .LBB0_330
	v_pk_mul_f32 v[12:13], v[2:3], v[2:3]
	s_nop 0
	s_nop 0
	s_nop 0
	v_pk_fma_f32 v[12:13], v[12:13], v[184:185], v[186:187]
	s_nop 0
	v_pk_mul_f32 v[12:13], v[12:13], v[2:3] neg_lo:[0,1] neg_hi:[0,1]
	s_nop 0
	v_exp_f32_e32 v12, v12
	v_exp_f32_e32 v13, v13
	s_nop 0
	v_pk_add_f32 v[12:13], v[12:13], v[188:189]
	s_nop 0
	v_rcp_f32_e32 v12, v12
	v_rcp_f32_e32 v13, v13
	s_nop 0
	s_nop 0
	v_pk_mul_f32 v[2:3], v[2:3], v[12:13]
	v_pk_mul_f32 v[12:13], v[4:5], v[4:5]
	s_nop 0
	s_nop 0
	s_nop 0
	v_pk_fma_f32 v[12:13], v[12:13], v[184:185], v[186:187]
	s_nop 0
	v_pk_mul_f32 v[12:13], v[12:13], v[4:5] neg_lo:[0,1] neg_hi:[0,1]
	s_nop 0
	v_exp_f32_e32 v12, v12
	v_exp_f32_e32 v13, v13
	s_nop 0
	v_pk_add_f32 v[12:13], v[12:13], v[188:189]
	s_nop 0
	v_rcp_f32_e32 v12, v12
	v_rcp_f32_e32 v13, v13
	s_nop 0
	s_nop 0
	v_pk_mul_f32 v[4:5], v[4:5], v[12:13]

; __device__ void attn_item(const Params& p, int layer, int item, int dry) {
;     ...
;   for (int i = 0; i < 4; ++i) {
;     int idx = tid + 512 * i;
;     int m = idx >> 3, d0 = (idx & 7) * 8;
;     uint4 uk = *(const uint4*)(kvs + (size_t)m * 1024 + h * 64 + d0);
;     *(uint4*)(Ks + m * 72 + d0) = uk;
;     uint4 uv = *(const uint4*)(kvs + (size_t)m * 1024 + 256 + h * 64 + d0);
;     unsigned uu[4] = {uv.x, uv.y, uv.z, uv.w};
;     for (int j = 0; j < 8; ++j) Vt[(d0 + j) * 264 + m] = (bf16_t)((j & 1) ? (uu[j >> 1] >> 16) : (uu[j >> 1] & 0xffff));
;   }
;   __syncthreads();
;   const int t = tok0 + wid * 16 + r;
;   bf16_t* qp = cat + (size_t)t * 1024 + 768 + h * 64;
;   bf16x8 qf[2];
;   qf[0] = *(const bf16x8*)(qp + quad * 8);
;   qf[1] = *(const bf16x8*)(qp + 32 + quad * 8);
.LBB0_1348:
	s_and_b64 vcc, exec, s[4:5]
	s_cbranch_vccz .LBB0_1365
	s_lshl_b32 s4, s27, 5
	s_and_b32 s6, s4, 0xffffff80
	s_addk_i32 s4, 0x8000
	s_lshr_b32 s4, s4, 12
	s_ashr_i32 s5, s27, 6
	s_add_i32 s4, s4, 16
	s_cmp_lt_i32 s6, 0x8000
	v_mov_b32_e32 v44, v208
	s_cselect_b32 s4, s5, s4
	s_ashr_i32 s5, s4, 31
	v_add_u32_e32 v10, 0x200, v44
	v_add_u32_e32 v18, 0x400, v44
	v_add_u32_e32 v26, 0x600, v44
	s_lshl_b64 s[4:5], s[4:5], 19
	v_ashrrev_i32_e32 v34, 3, v44
	v_ashrrev_i32_e32 v36, 3, v10
	v_ashrrev_i32_e32 v38, 3, v18
	v_ashrrev_i32_e32 v40, 3, v26
	s_add_u32 s4, s77, s4
	v_ashrrev_i32_e32 v35, 31, v34
	v_ashrrev_i32_e32 v37, 31, v36
	v_ashrrev_i32_e32 v39, 31, v38
	v_ashrrev_i32_e32 v41, 31, v40
	s_addc_u32 s5, s78, s5
	v_lshlrev_b32_e32 v0, 3, v44
	v_lshlrev_b64 v[2:3], 11, v[34:35]
	s_lshl_b32 s7, s27, 7
	v_lshlrev_b64 v[10:11], 11, v[36:37]
	v_lshlrev_b64 v[18:19], 11, v[38:39]
	v_lshlrev_b64 v[26:27], 11, v[40:41]
	v_and_b32_e32 v42, 56, v0
	v_lshl_add_u64 v[2:3], s[4:5], 0, v[2:3]
	s_and_b32 s66, s7, 0x180
	v_lshl_add_u64 v[10:11], s[4:5], 0, v[10:11]
	v_lshl_add_u64 v[18:19], s[4:5], 0, v[18:19]
	v_lshl_add_u64 v[26:27], s[4:5], 0, v[26:27]
	v_lshlrev_b32_e32 v0, 1, v42
	v_lshl_add_u64 v[2:3], v[2:3], 0, s[66:67]
	v_lshl_add_u64 v[10:11], v[10:11], 0, s[66:67]
	v_lshl_add_u64 v[18:19], v[18:19], 0, s[66:67]
	v_lshl_add_u64 v[26:27], v[26:27], 0, s[66:67]
	v_lshl_add_u64 v[6:7], v[2:3], 0, v[0:1]
	v_lshl_add_u64 v[14:15], v[10:11], 0, v[0:1]
	v_lshl_add_u64 v[22:23], v[18:19], 0, v[0:1]
	v_lshl_add_u64 v[30:31], v[26:27], 0, v[0:1]
	global_load_dwordx4 v[2:5], v[6:7], off
	s_nop 0
	global_load_dwordx4 v[6:9], v[6:7], off offset:512
	s_nop 0
	global_load_dwordx4 v[10:13], v[14:15], off
	s_nop 0
	global_load_dwordx4 v[14:17], v[14:15], off offset:512
	s_nop 0
	global_load_dwordx4 v[18:21], v[22:23], off
	s_nop 0
	global_load_dwordx4 v[22:25], v[22:23], off offset:512
	s_nop 0
	global_load_dwordx4 v[26:29], v[30:31], off
	s_nop 0
	global_load_dwordx4 v[30:33], v[30:31], off offset:512
	s_movk_i32 s7, 0x90
	v_mul_u32_u24_e32 v41, 0x251, v42
	v_mad_u64_u32 v[42:43], s[4:5], v34, s7, v[0:1]
	v_lshl_add_u32 v43, v34, 1, v41
	v_mad_u64_u32 v[34:35], s[4:5], v36, s7, v[0:1]
	v_lshl_add_u32 v35, v36, 1, v41
	v_mad_u64_u32 v[36:37], s[4:5], v38, s7, v[0:1]
	v_lshl_add_u32 v37, v38, 1, v41
	v_mad_u64_u32 v[38:39], s[4:5], v40, s7, v[0:1]
	v_lshl_add_u32 v0, v40, 1, v41
	v_and_b32_e32 v60, 15, v44
	v_bfe_u32 v61, v44, 4, 2
	s_mov_b64 s[4:5], 0xe1a6600
	s_waitcnt vmcnt(7)
	ds_write_b128 v42, v[2:5]
	s_waitcnt vmcnt(6)
	ds_write_b16 v43, v6 offset:36864
	ds_write_b16_d16_hi v43, v6 offset:37456
	ds_write_b16 v43, v7 offset:38048
	ds_write_b16_d16_hi v43, v7 offset:38640
	ds_write_b16 v43, v8 offset:39232
	ds_write_b16_d16_hi v43, v8 offset:39824
	ds_write_b16 v43, v9 offset:40416
	ds_write_b16_d16_hi v43, v9 offset:41008
	s_waitcnt vmcnt(5)
	ds_write_b128 v34, v[10:13]
	s_waitcnt vmcnt(4)
	ds_write_b16 v35, v14 offset:36864
	ds_write_b16_d16_hi v35, v14 offset:37456
	ds_write_b16 v35, v15 offset:38048
	ds_write_b16_d16_hi v35, v15 offset:38640
	ds_write_b16 v35, v16 offset:39232
	ds_write_b16_d16_hi v35, v16 offset:39824
	ds_write_b16 v35, v17 offset:40416
	ds_write_b16_d16_hi v35, v17 offset:41008
	s_waitcnt vmcnt(3)
	ds_write_b128 v36, v[18:21]
	s_waitcnt vmcnt(2)
	ds_write_b16 v37, v22 offset:36864
	ds_write_b16_d16_hi v37, v22 offset:37456
	ds_write_b16 v37, v23 offset:38048
	ds_write_b16_d16_hi v37, v23 offset:38640
	ds_write_b16 v37, v24 offset:39232
	ds_write_b16_d16_hi v37, v24 offset:39824
	ds_write_b16 v37, v25 offset:40416
	ds_write_b16_d16_hi v37, v25 offset:41008
	s_waitcnt vmcnt(1)
	ds_write_b128 v38, v[26:29]
	s_waitcnt vmcnt(0)
	ds_write_b16 v0, v30 offset:36864
	ds_write_b16_d16_hi v0, v30 offset:37456
	ds_write_b16 v0, v31 offset:38048
	ds_write_b16_d16_hi v0, v31 offset:38640
	ds_write_b16 v0, v32 offset:39232
	ds_write_b16_d16_hi v0, v32 offset:39824
	ds_write_b16 v0, v33 offset:40416
	ds_write_b16_d16_hi v0, v33 offset:41008
	v_ashrrev_i32_e32 v0, 2, v44
	v_and_b32_e32 v0, -16, v0
	v_add_u32_e32 v0, s6, v0
	v_or_b32_e32 v2, v0, v60
	v_ashrrev_i32_e32 v3, 31, v2
	v_lshlrev_b64 v[2:3], 11, v[2:3]
	v_lshl_add_u64 v[2:3], s[14:15], 0, v[2:3]
	v_lshl_add_u64 v[2:3], v[2:3], 0, s[66:67]
	v_lshl_add_u64 v[54:55], v[2:3], 0, s[4:5]
	v_lshlrev_b32_e32 v0, 4, v61
	v_lshl_add_u64 v[34:35], v[54:55], 0, v[0:1]
	global_load_dwordx4 v[2:5], v[34:35], off
	global_load_dwordx4 v[56:59], v[34:35], off offset:64
	s_waitcnt lgkmcnt(0)
	s_barrier
; __device__ void attn_item(const Params& p, int layer, int item, int dry) {
;     ...
;   f32x4 s[16];
;   for (int mt = 0; mt < 16; ++mt) {
;     s[mt] = f32x4{0.f, 0.f, 0.f, 0.f};
;     for (int ks = 0; ks < 2; ++ks) {
;       bf16x8 a = *(const bf16x8*)(Ks + (mt * 16 + r) * 72 + ks * 32 + quad * 8);
;       s[mt] = __builtin_amdgcn_mfma_f32_16x16x32_bf16(a, qf[ks], s[mt], 0, 0, 0);
;     }
;   }
;   float mx = -1e30f;
;   for (int mt = 0; mt < 16; ++mt)
;     for (int j = 0; j < 4; ++j) mx = fmaxf(mx, s[mt][j]);
;   mx = fmaxf(mx, __shfl_xor(mx, 16));
;   mx = fmaxf(mx, __shfl_xor(mx, 32));
	v_mad_u32_u24 v98, v60, s7, v0
	ds_read_b128 v[38:41], v98 offset:18432
	ds_read_b128 v[6:9], v98
	ds_read_b128 v[10:13], v98 offset:2304
	ds_read_b128 v[14:17], v98 offset:4608
	ds_read_b128 v[18:21], v98 offset:6912
	ds_read_b128 v[22:25], v98 offset:9216
	ds_read_b128 v[26:29], v98 offset:11520
	ds_read_b128 v[30:33], v98 offset:13824
	ds_read_b128 v[34:37], v98 offset:16128
	s_mov_b32 s4, 0xf149f2ca
	s_waitcnt vmcnt(1) lgkmcnt(8)
	v_mfma_f32_16x16x32_bf16 v[62:65], v[38:41], v[2:5], 0
	ds_read_b128 v[38:41], v98 offset:20736
	s_waitcnt lgkmcnt(0)
	v_mfma_f32_16x16x32_bf16 v[66:69], v[38:41], v[2:5], 0
	ds_read_b128 v[38:41], v98 offset:23040
	s_waitcnt lgkmcnt(0)
	v_mfma_f32_16x16x32_bf16 v[70:73], v[38:41], v[2:5], 0
	ds_read_b128 v[38:41], v98 offset:25344
	s_waitcnt lgkmcnt(0)
	v_mfma_f32_16x16x32_bf16 v[74:77], v[38:41], v[2:5], 0
	ds_read_b128 v[38:41], v98 offset:27648
	s_waitcnt lgkmcnt(0)
	v_mfma_f32_16x16x32_bf16 v[78:81], v[38:41], v[2:5], 0
	ds_read_b128 v[38:41], v98 offset:29952
	s_waitcnt lgkmcnt(0)
	v_mfma_f32_16x16x32_bf16 v[82:85], v[38:41], v[2:5], 0
	ds_read_b128 v[38:41], v98 offset:64
	v_mfma_f32_16x16x32_bf16 v[6:9], v[6:9], v[2:5], 0
	s_waitcnt vmcnt(0) lgkmcnt(0)
	v_mfma_f32_16x16x32_bf16 v[86:89], v[38:41], v[56:59], v[6:9]
	s_nop 5
	ds_read_b128 v[6:9], v98 offset:2368
	v_mfma_f32_16x16x32_bf16 v[10:13], v[10:13], v[2:5], 0
	s_waitcnt lgkmcnt(0)
	v_mfma_f32_16x16x32_bf16 v[90:93], v[6:9], v[56:59], v[10:13]
	ds_read_b128 v[6:9], v98 offset:4672
	v_mfma_f32_16x16x32_bf16 v[14:17], v[14:17], v[2:5], 0
	s_waitcnt lgkmcnt(0)
	v_mfma_f32_16x16x32_bf16 v[94:97], v[6:9], v[56:59], v[14:17]
	ds_read_b128 v[6:9], v98 offset:6976
	v_mfma_f32_16x16x32_bf16 v[18:21], v[18:21], v[2:5], 0
	s_waitcnt lgkmcnt(0)
	v_mfma_f32_16x16x32_bf16 v[50:53], v[6:9], v[56:59], v[18:21]
	ds_read_b128 v[6:9], v98 offset:9280
	v_mfma_f32_16x16x32_bf16 v[22:25], v[22:25], v[2:5], 0
	s_waitcnt lgkmcnt(0)
	v_mfma_f32_16x16x32_bf16 v[46:49], v[6:9], v[56:59], v[22:25]
	ds_read_b128 v[6:9], v98 offset:11584
	v_mfma_f32_16x16x32_bf16 v[26:29], v[26:29], v[2:5], 0
	s_waitcnt lgkmcnt(0)
	v_mfma_f32_16x16x32_bf16 v[42:45], v[6:9], v[56:59], v[26:29]
	ds_read_b128 v[6:9], v98 offset:13888
	v_mfma_f32_16x16x32_bf16 v[30:33], v[30:33], v[2:5], 0
	s_waitcnt lgkmcnt(0)
	v_mfma_f32_16x16x32_bf16 v[38:41], v[6:9], v[56:59], v[30:33]
	ds_read_b128 v[6:9], v98 offset:16192
	v_mfma_f32_16x16x32_bf16 v[34:37], v[34:37], v[2:5], 0
	s_waitcnt lgkmcnt(0)
	v_mfma_f32_16x16x32_bf16 v[34:37], v[6:9], v[56:59], v[34:37]
	ds_read_b128 v[6:9], v98 offset:18496
	s_waitcnt lgkmcnt(0)
	v_mfma_f32_16x16x32_bf16 v[30:33], v[6:9], v[56:59], v[62:65]
	ds_read_b128 v[6:9], v98 offset:20800
	s_nop 1
	ds_read_b128 v[62:65], v98 offset:32320
	s_waitcnt lgkmcnt(1)
	v_mfma_f32_16x16x32_bf16 v[26:29], v[6:9], v[56:59], v[66:69]
	ds_read_b128 v[6:9], v98 offset:23104
	s_waitcnt lgkmcnt(0)
	v_mfma_f32_16x16x32_bf16 v[22:25], v[6:9], v[56:59], v[70:73]
	ds_read_b128 v[6:9], v98 offset:25408
	s_waitcnt lgkmcnt(0)
	v_mfma_f32_16x16x32_bf16 v[18:21], v[6:9], v[56:59], v[74:77]
	ds_read_b128 v[6:9], v98 offset:27712
	s_waitcnt lgkmcnt(0)
	v_mfma_f32_16x16x32_bf16 v[14:17], v[6:9], v[56:59], v[78:81]
	ds_read_b128 v[6:9], v98 offset:30016
	s_waitcnt lgkmcnt(0)
	v_mfma_f32_16x16x32_bf16 v[10:13], v[6:9], v[56:59], v[82:85]
	ds_read_b128 v[6:9], v98 offset:32256
	s_waitcnt lgkmcnt(0)
	v_mfma_f32_16x16x32_bf16 v[6:9], v[6:9], v[2:5], 0
	v_mfma_f32_16x16x32_bf16 v[6:9], v[62:65], v[56:59], v[6:9]
	ds_read_b128 v[62:65], v98 offset:34560
	s_waitcnt lgkmcnt(0)
	v_mfma_f32_16x16x32_bf16 v[2:5], v[62:65], v[2:5], 0
	ds_read_b128 v[62:65], v98 offset:34624
	s_waitcnt lgkmcnt(0)
	v_mfma_f32_16x16x32_bf16 v[2:5], v[62:65], v[56:59], v[2:5]
	v_max3_f32 v56, v86, s4, v87
	v_max3_f32 v56, v56, v88, v89
	v_max3_f32 v56, v56, v90, v91
	v_max3_f32 v56, v56, v92, v93
	v_max3_f32 v56, v56, v94, v95
	v_max3_f32 v56, v56, v96, v97
	v_max3_f32 v56, v56, v50, v51
	v_max3_f32 v56, v56, v52, v53
	v_max3_f32 v56, v56, v46, v47
	v_max3_f32 v56, v56, v48, v49
	v_max3_f32 v56, v56, v42, v43
	v_max3_f32 v56, v56, v44, v45
	v_max3_f32 v56, v56, v38, v39
	v_max3_f32 v56, v56, v40, v41
	v_max3_f32 v56, v56, v34, v35
	v_max3_f32 v56, v56, v36, v37
	v_max3_f32 v56, v56, v30, v31
	v_max3_f32 v56, v56, v32, v33
	v_max3_f32 v56, v56, v26, v27
	v_max3_f32 v56, v56, v28, v29
	v_max3_f32 v56, v56, v22, v23
	v_max3_f32 v56, v56, v24, v25
	v_max3_f32 v56, v56, v18, v19
	v_max3_f32 v56, v56, v20, v21
	v_max3_f32 v56, v56, v14, v15
	v_max3_f32 v56, v56, v16, v17
	v_max3_f32 v56, v56, v10, v11
	v_max3_f32 v56, v56, v12, v13
	v_and_b32_e32 v58, 64, v228
	v_max3_f32 v56, v56, v6, v7
	v_xor_b32_e32 v57, 16, v228
	v_add_u32_e32 v59, 64, v58
	v_max3_f32 v56, v56, v8, v9
	v_cmp_lt_i32_e32 vcc, v57, v59
	v_max3_f32 v56, v56, v2, v3
	v_max3_f32 v56, v56, v4, v5
	v_cndmask_b32_e32 v57, v228, v57, vcc
	v_lshlrev_b32_e32 v58, 2, v57
	ds_bpermute_b32 v57, v58, v56
	s_movk_i32 s4, 0x210
	s_waitcnt lgkmcnt(0)
	v_max_f32_e32 v57, v57, v57
	v_max_f32_e32 v62, v56, v57
	v_xor_b32_e32 v56, 32, v228
	v_cmp_lt_i32_e32 vcc, v56, v59
	s_nop 1
	v_cndmask_b32_e32 v56, v228, v56, vcc
	v_lshlrev_b32_e32 v57, 2, v56
	ds_bpermute_b32 v59, v57, v62
	v_lshlrev_b32_e32 v56, 3, v61
	v_sub_u32_e32 v0, v0, v56
	s_andn2_b64 vcc, exec, s[24:25]
	s_waitcnt lgkmcnt(0)
; __device__ void attn_item(const Params& p, int layer, int item, int dry) {
;     ...
;   float sum = 0.f;
;   for (int mt = 0; mt < 16; ++mt)
;     for (int j = 0; j < 4; ++j) {
;       float e = __expf((s[mt][j] - mx) * 0.125f);
;       s[mt][j] = e;
;       sum += e;
;     }
	v_max_f32_e32 v59, v59, v59
	v_max_f32_e32 v59, v62, v59
	v_sub_f32_e32 v61, v86, v59
	v_mul_f32_e32 v61, 0x3e38aa3b, v61
	v_exp_f32_e32 v65, v61
	v_sub_f32_e32 v61, v87, v59
	v_mul_f32_e32 v61, 0x3e38aa3b, v61
	v_sub_f32_e32 v62, v90, v59
	v_mul_f32_e32 v62, 0x3e38aa3b, v62
	v_exp_f32_e32 v66, v61
	v_sub_f32_e32 v61, v88, v59
	v_mul_f32_e32 v61, 0x3e38aa3b, v61
	v_exp_f32_e32 v68, v62
	v_sub_f32_e32 v62, v91, v59
	v_mul_f32_e32 v62, 0x3e38aa3b, v62
	v_exp_f32_e32 v67, v61
	v_sub_f32_e32 v61, v89, v59
	v_mul_f32_e32 v61, 0x3e38aa3b, v61
	v_exp_f32_e32 v75, v62
	v_sub_f32_e32 v62, v92, v59
	v_mul_f32_e32 v62, 0x3e38aa3b, v62
	v_exp_f32_e32 v74, v61
	v_add_f32_e32 v61, 0, v65
	v_exp_f32_e32 v69, v62
	v_sub_f32_e32 v62, v93, v59
	v_add_f32_e32 v61, v66, v61
	v_mul_f32_e32 v62, 0x3e38aa3b, v62
	v_add_f32_e32 v61, v67, v61
	v_add_f32_e32 v61, v74, v61
	v_exp_f32_e32 v70, v62
	v_add_f32_e32 v61, v68, v61
	v_add_f32_e32 v61, v75, v61
	v_sub_f32_e32 v50, v50, v59
	v_add_f32_e32 v61, v69, v61
	v_mul_f32_e32 v50, 0x3e38aa3b, v50
	v_add_f32_e32 v71, v70, v61
	v_sub_f32_e32 v61, v94, v59
	v_mul_f32_e32 v61, 0x3e38aa3b, v61
	v_sub_f32_e32 v62, v95, v59
	v_exp_f32_e32 v90, v50
	v_sub_f32_e32 v50, v51, v59
	v_mul_f32_e32 v62, 0x3e38aa3b, v62
	v_sub_f32_e32 v63, v96, v59
	v_mul_f32_e32 v50, 0x3e38aa3b, v50
	v_exp_f32_e32 v61, v61
	v_mul_f32_e32 v63, 0x3e38aa3b, v63
	v_sub_f32_e32 v64, v97, v59
	v_exp_f32_e32 v62, v62
	v_mul_f32_e32 v64, 0x3e38aa3b, v64
	v_exp_f32_e32 v91, v50
	v_sub_f32_e32 v50, v52, v59
	v_exp_f32_e32 v63, v63
	v_mul_f32_e32 v50, 0x3e38aa3b, v50
	v_exp_f32_e32 v64, v64
	v_add_f32_e32 v71, v61, v71
	v_exp_f32_e32 v92, v50
	v_sub_f32_e32 v50, v53, v59
	v_add_f32_e32 v71, v62, v71
	v_mul_f32_e32 v50, 0x3e38aa3b, v50
	v_sub_f32_e32 v46, v46, v59
	v_add_f32_e32 v71, v63, v71
	v_mul_f32_e32 v46, 0x3e38aa3b, v46
	v_sub_f32_e32 v47, v47, v59
	v_add_f32_e32 v71, v64, v71
	v_exp_f32_e32 v53, v50
	v_mul_f32_e32 v47, 0x3e38aa3b, v47
	v_sub_f32_e32 v48, v48, v59
	v_add_f32_e32 v50, v90, v71
	v_exp_f32_e32 v46, v46
	v_mul_f32_e32 v48, 0x3e38aa3b, v48
	v_sub_f32_e32 v49, v49, v59
	v_add_f32_e32 v50, v91, v50
	v_exp_f32_e32 v47, v47
	v_mul_f32_e32 v49, 0x3e38aa3b, v49
	v_add_f32_e32 v50, v92, v50
	v_exp_f32_e32 v48, v48
	v_add_f32_e32 v50, v53, v50
	v_exp_f32_e32 v49, v49
	v_add_f32_e32 v50, v46, v50
	v_sub_f32_e32 v42, v42, v59
	v_add_f32_e32 v50, v47, v50
	v_mul_f32_e32 v42, 0x3e38aa3b, v42
	v_add_f32_e32 v50, v48, v50
	v_add_f32_e32 v71, v49, v50
	v_exp_f32_e32 v50, v42
	v_sub_f32_e32 v42, v43, v59
	v_mul_f32_e32 v42, 0x3e38aa3b, v42
	v_exp_f32_e32 v51, v42
	v_sub_f32_e32 v42, v44, v59
	v_mul_f32_e32 v42, 0x3e38aa3b, v42
	v_exp_f32_e32 v52, v42
	v_sub_f32_e32 v42, v45, v59
	v_mul_f32_e32 v42, 0x3e38aa3b, v42
	v_sub_f32_e32 v38, v38, v59
	v_mul_f32_e32 v38, 0x3e38aa3b, v38
	v_sub_f32_e32 v39, v39, v59
	v_exp_f32_e32 v45, v42
	v_mul_f32_e32 v39, 0x3e38aa3b, v39
	v_sub_f32_e32 v40, v40, v59
	v_add_f32_e32 v42, v50, v71
	v_exp_f32_e32 v38, v38
	v_mul_f32_e32 v40, 0x3e38aa3b, v40
	v_sub_f32_e32 v41, v41, v59
	v_add_f32_e32 v42, v51, v42
	v_exp_f32_e32 v39, v39
	v_mul_f32_e32 v41, 0x3e38aa3b, v41
	v_add_f32_e32 v42, v52, v42
	v_exp_f32_e32 v40, v40
	v_add_f32_e32 v42, v45, v42
	v_exp_f32_e32 v41, v41
	v_add_f32_e32 v42, v38, v42
	v_sub_f32_e32 v34, v34, v59
	v_add_f32_e32 v42, v39, v42
	v_mul_f32_e32 v34, 0x3e38aa3b, v34
	v_add_f32_e32 v42, v40, v42
	v_add_f32_e32 v71, v41, v42
	v_exp_f32_e32 v42, v34
	v_sub_f32_e32 v34, v35, v59
	v_mul_f32_e32 v34, 0x3e38aa3b, v34
	v_exp_f32_e32 v43, v34
	v_sub_f32_e32 v34, v36, v59
	v_mul_f32_e32 v34, 0x3e38aa3b, v34
	v_exp_f32_e32 v44, v34
	v_sub_f32_e32 v34, v37, v59
	v_mul_f32_e32 v34, 0x3e38aa3b, v34
	v_sub_f32_e32 v30, v30, v59
	v_mul_f32_e32 v30, 0x3e38aa3b, v30
	v_sub_f32_e32 v31, v31, v59
	v_exp_f32_e32 v37, v34
	v_mul_f32_e32 v31, 0x3e38aa3b, v31
	v_sub_f32_e32 v32, v32, v59
	v_add_f32_e32 v34, v42, v71
	v_exp_f32_e32 v30, v30
	v_mul_f32_e32 v32, 0x3e38aa3b, v32
	v_sub_f32_e32 v33, v33, v59
	v_add_f32_e32 v34, v43, v34
	v_exp_f32_e32 v31, v31
	v_mul_f32_e32 v33, 0x3e38aa3b, v33
	v_add_f32_e32 v34, v44, v34
	v_exp_f32_e32 v32, v32
	v_add_f32_e32 v34, v37, v34
	v_exp_f32_e32 v33, v33
	v_add_f32_e32 v34, v30, v34
	v_sub_f32_e32 v26, v26, v59
	v_add_f32_e32 v34, v31, v34
	v_mul_f32_e32 v26, 0x3e38aa3b, v26
	v_add_f32_e32 v34, v32, v34
	v_add_f32_e32 v71, v33, v34
	v_exp_f32_e32 v34, v26
	v_sub_f32_e32 v26, v27, v59
	v_mul_f32_e32 v26, 0x3e38aa3b, v26
	v_exp_f32_e32 v35, v26
	v_sub_f32_e32 v26, v28, v59
	v_mul_f32_e32 v26, 0x3e38aa3b, v26
	v_exp_f32_e32 v28, v26
	v_sub_f32_e32 v26, v29, v59
	v_mul_f32_e32 v26, 0x3e38aa3b, v26
	v_sub_f32_e32 v22, v22, v59
	v_mul_f32_e32 v22, 0x3e38aa3b, v22
	v_sub_f32_e32 v23, v23, v59
	v_exp_f32_e32 v36, v26
	v_mul_f32_e32 v23, 0x3e38aa3b, v23
	v_sub_f32_e32 v24, v24, v59
	v_add_f32_e32 v26, v34, v71
	v_exp_f32_e32 v22, v22
	v_mul_f32_e32 v24, 0x3e38aa3b, v24
	v_sub_f32_e32 v25, v25, v59
	v_add_f32_e32 v26, v35, v26
	v_exp_f32_e32 v23, v23
	v_mul_f32_e32 v25, 0x3e38aa3b, v25
	v_add_f32_e32 v26, v28, v26
	v_exp_f32_e32 v24, v24
	v_add_f32_e32 v26, v36, v26
	v_exp_f32_e32 v25, v25
	v_add_f32_e32 v26, v22, v26
	v_sub_f32_e32 v18, v18, v59
	v_sub_f32_e32 v20, v20, v59
	v_add_f32_e32 v26, v23, v26
	v_mul_f32_e32 v18, 0x3e38aa3b, v18
	v_sub_f32_e32 v19, v19, v59
	v_mul_f32_e32 v20, 0x3e38aa3b, v20
	v_add_f32_e32 v26, v24, v26
	v_mul_f32_e32 v19, 0x3e38aa3b, v19
	v_add_f32_e32 v29, v25, v26
	v_exp_f32_e32 v18, v18
	v_exp_f32_e32 v26, v20
	v_sub_f32_e32 v20, v21, v59
	v_exp_f32_e32 v19, v19
	v_mul_f32_e32 v20, 0x3e38aa3b, v20
	v_sub_f32_e32 v14, v14, v59
	v_mul_f32_e32 v14, 0x3e38aa3b, v14
; __device__ __forceinline__ unsigned short f2bf(float f) { return (unsigned short)(pack2(f, 0.f) & 0xffffu); }
; __device__ void attn_item(const Params& p, int layer, int item, int dry) {
;     ...
;   float sum = 0.f;
;   for (int mt = 0; mt < 16; ++mt)
;     for (int j = 0; j < 4; ++j) {
;       float e = __expf((s[mt][j] - mx) * 0.125f);
;       s[mt][j] = e;
;       sum += e;
;     }
;   sum += __shfl_xor(sum, 16);
;   sum += __shfl_xor(sum, 32);
;   const float inv = 1.f / sum;
;   f32x4 o[4] = {};
;   for (int ks = 0; ks < 8; ++ks) {
;     bf16x8 pb;
;     for (int j = 0; j < 4; ++j) {
;       pb[j] = (short)f2bf(s[2 * ks][j]);
;       pb[4 + j] = (short)f2bf(s[2 * ks + 1][j]);
;     }
;     for (int dt = 0; dt < 4; ++dt) {
;       const bf16_t* vp = Vt + (dt * 16 + r) * 264 + ks * 32 + quad * 4;
;       uint2 v0 = *(const uint2*)vp, v1 = *(const uint2*)(vp + 16);
;       bf16x8 av;
;       av[0] = (short)(v0.x & 0xffff); av[1] = (short)(v0.x >> 16); av[2] = (short)(v0.y & 0xffff); av[3] = (short)(v0.y >> 16);
;       av[4] = (short)(v1.x & 0xffff); av[5] = (short)(v1.x >> 16); av[6] = (short)(v1.y & 0xffff); av[7] = (short)(v1.y >> 16);
;       o[dt] = __builtin_amdgcn_mfma_f32_16x16x32_bf16(av, pb, o[dt], 0, 0, 0);
;     }
;   }
	v_sub_f32_e32 v15, v15, v59
	v_exp_f32_e32 v27, v20
	v_mul_f32_e32 v15, 0x3e38aa3b, v15
	v_sub_f32_e32 v16, v16, v59
	v_add_f32_e32 v20, v18, v29
	v_exp_f32_e32 v14, v14
	v_mul_f32_e32 v16, 0x3e38aa3b, v16
	v_sub_f32_e32 v17, v17, v59
	v_add_f32_e32 v20, v19, v20
	v_exp_f32_e32 v15, v15
	v_mul_f32_e32 v17, 0x3e38aa3b, v17
	v_sub_f32_e32 v10, v10, v59
	v_add_f32_e32 v20, v26, v20
	v_exp_f32_e32 v16, v16
	v_mul_f32_e32 v10, 0x3e38aa3b, v10
	v_sub_f32_e32 v11, v11, v59
	v_add_f32_e32 v20, v27, v20
	v_exp_f32_e32 v17, v17
	v_mul_f32_e32 v11, 0x3e38aa3b, v11
	v_sub_f32_e32 v12, v12, v59
	v_add_f32_e32 v20, v14, v20
	v_exp_f32_e32 v10, v10
	v_mul_f32_e32 v12, 0x3e38aa3b, v12
	v_sub_f32_e32 v13, v13, v59
	v_add_f32_e32 v20, v15, v20
	v_exp_f32_e32 v11, v11
	v_mul_f32_e32 v13, 0x3e38aa3b, v13
	v_add_f32_e32 v20, v16, v20
	v_exp_f32_e32 v12, v12
	v_add_f32_e32 v20, v17, v20
	v_exp_f32_e32 v13, v13
	v_add_f32_e32 v20, v10, v20
	v_add_f32_e32 v20, v11, v20
	v_add_f32_e32 v20, v12, v20
	v_add_f32_e32 v86, v13, v20
	v_sub_f32_e32 v7, v7, v59
	v_mul_u32_u24_e32 v176, 0x250, v60
	v_lshrrev_b32_e32 v177, 3, v60
	v_add_u32_e32 v20, v176, v0
	v_lshl_add_u32 v20, v177, 3, v20
	v_mul_f32_e32 v29, 0x3e38aa3b, v7
	v_add_u32_e32 v21, 0x9000, v20
	v_add_u32_e32 v7, 0xb410, v20
	v_add_u32_e32 v0, 0xd820, v20
	v_add_u32_e32 v20, 0xfc30, v20
	v_cvt_pk_bf16_f32 v69, v69, v70
	ds_read2_b64 v[70:73], v21 offset1:4
	v_cvt_pk_bf16_f32 v68, v68, v75
	v_cvt_pk_bf16_f32 v67, v67, v74
	ds_read2_b64 v[74:77], v7 offset0:32 offset1:36
	ds_read2_b64 v[78:81], v0 offset0:64 offset1:68
	ds_read2_b64 v[82:85], v20 offset0:96 offset1:100
	v_sub_f32_e32 v6, v6, v59
	v_mul_f32_e32 v6, 0x3e38aa3b, v6
	v_exp_f32_e32 v6, v6
	s_waitcnt lgkmcnt(3)
	v_bfi_b32 v72, s65, v72, v72
	s_waitcnt lgkmcnt(2)
	v_bfi_b32 v76, s65, v76, v76
	s_waitcnt lgkmcnt(1)
	v_bfi_b32 v80, s65, v80, v80
	s_waitcnt lgkmcnt(0)
	v_bfi_b32 v84, s65, v84, v84
	v_exp_f32_e32 v29, v29
	v_cvt_pk_bf16_f32 v66, v65, v66
	v_add_f32_e32 v60, v6, v86
	ds_read2_b64 v[86:89], v21 offset0:8 offset1:12
	v_mfma_f32_16x16x32_bf16 v[70:73], v[70:73], v[66:69], 0
	v_add_f32_e32 v94, v29, v60
	v_sub_f32_e32 v8, v8, v59
	v_mul_f32_e32 v8, 0x3e38aa3b, v8
	v_mfma_f32_16x16x32_bf16 v[74:77], v[74:77], v[66:69], 0
	s_waitcnt lgkmcnt(0)
	v_bfi_b32 v88, s65, v88, v88
	v_sub_f32_e32 v2, v2, v59
	v_mfma_f32_16x16x32_bf16 v[78:81], v[78:81], v[66:69], 0
	v_mul_f32_e32 v2, 0x3e38aa3b, v2
	v_cvt_pk_bf16_f32 v27, v26, v27
	v_mfma_f32_16x16x32_bf16 v[66:69], v[82:85], v[66:69], 0
	v_cvt_pk_bf16_f32 v83, v63, v64
	v_cvt_pk_bf16_f32 v82, v61, v62
	ds_read2_b64 v[60:63], v0 offset0:72 offset1:76
	v_cvt_pk_bf16_f32 v85, v92, v53
	v_cvt_pk_bf16_f32 v84, v90, v91
	ds_read2_b64 v[90:93], v7 offset0:40 offset1:44
	v_cvt_pk_bf16_f32 v53, v52, v45
	s_waitcnt lgkmcnt(1)
	v_bfi_b32 v62, s65, v62, v62
	v_mfma_f32_16x16x32_bf16 v[70:73], v[86:89], v[82:85], v[70:73]
	ds_read2_b64 v[86:89], v20 offset0:104 offset1:108
	v_cvt_pk_bf16_f32 v52, v50, v51
	v_cvt_pk_bf16_f32 v51, v48, v49
	v_mfma_f32_16x16x32_bf16 v[60:63], v[60:63], v[82:85], v[78:81]
	v_cvt_pk_bf16_f32 v50, v46, v47
	ds_read2_b64 v[46:49], v0 offset0:80 offset1:84
	s_waitcnt lgkmcnt(2)
	v_bfi_b32 v92, s65, v92, v92
	ds_read2_b64 v[78:81], v21 offset0:16 offset1:20
	s_waitcnt lgkmcnt(2)
	v_bfi_b32 v88, s65, v88, v88
	v_mfma_f32_16x16x32_bf16 v[74:77], v[90:93], v[82:85], v[74:77]
	s_waitcnt lgkmcnt(0)
	v_bfi_b32 v80, s65, v80, v80
	v_bfi_b32 v48, s65, v48, v48
	v_cvt_pk_bf16_f32 v45, v44, v37
	v_mfma_f32_16x16x32_bf16 v[64:67], v[86:89], v[82:85], v[66:69]
	ds_read2_b64 v[82:85], v7 offset0:48 offset1:52
	v_cvt_pk_bf16_f32 v44, v42, v43
	v_cvt_pk_bf16_f32 v43, v40, v41
	v_mfma_f32_16x16x32_bf16 v[68:71], v[78:81], v[50:53], v[70:73]
	ds_read2_b64 v[78:81], v20 offset0:112 offset1:116
	v_cvt_pk_bf16_f32 v42, v38, v39
	ds_read2_b64 v[38:41], v0 offset0:88 offset1:92
	v_mfma_f32_16x16x32_bf16 v[46:49], v[46:49], v[50:53], v[60:63]
	s_waitcnt lgkmcnt(2)
	v_bfi_b32 v84, s65, v84, v84
	s_waitcnt lgkmcnt(1)
	v_bfi_b32 v80, s65, v80, v80
	v_cvt_pk_bf16_f32 v37, v28, v36
	ds_read2_b64 v[60:63], v21 offset0:24 offset1:28
	s_waitcnt lgkmcnt(1)
	v_bfi_b32 v40, s65, v40, v40
	v_mfma_f32_16x16x32_bf16 v[72:75], v[82:85], v[50:53], v[74:77]
	v_cvt_pk_bf16_f32 v36, v34, v35
	v_cvt_pk_bf16_f32 v35, v32, v33
	s_waitcnt lgkmcnt(0)
	v_bfi_b32 v62, s65, v62, v62
	v_mfma_f32_16x16x32_bf16 v[50:53], v[78:81], v[50:53], v[64:67]
	v_cvt_pk_bf16_f32 v34, v30, v31
	ds_read2_b64 v[30:33], v0 offset0:96 offset1:100
	v_exp_f32_e32 v90, v8
	ds_read2_b64 v[64:67], v7 offset0:56 offset1:60
	v_mfma_f32_16x16x32_bf16 v[60:63], v[60:63], v[42:45], v[68:71]
	v_sub_f32_e32 v8, v9, v59
	s_waitcnt lgkmcnt(1)
	v_bfi_b32 v32, s65, v32, v32
	v_mul_f32_e32 v8, 0x3e38aa3b, v8
	ds_read2_b64 v[68:71], v20 offset0:120 offset1:124
	v_mfma_f32_16x16x32_bf16 v[38:41], v[38:41], v[42:45], v[46:49]
	s_waitcnt lgkmcnt(1)
	v_bfi_b32 v66, s65, v66, v66
	v_exp_f32_e32 v9, v2
	ds_read2_b64 v[46:49], v21 offset0:32 offset1:36
	s_waitcnt lgkmcnt(1)
; __device__ __forceinline__ unsigned short f2bf(float f) { return (unsigned short)(pack2(f, 0.f) & 0xffffu); }
; __device__ void attn_item(const Params& p, int layer, int item, int dry) {
;     ...
;   sum += __shfl_xor(sum, 16);
;   sum += __shfl_xor(sum, 32);
;   const float inv = 1.f / sum;
;   f32x4 o[4] = {};
;   for (int ks = 0; ks < 8; ++ks) {
;     bf16x8 pb;
;     for (int j = 0; j < 4; ++j) {
;       pb[j] = (short)f2bf(s[2 * ks][j]);
;       pb[4 + j] = (short)f2bf(s[2 * ks + 1][j]);
;     }
;     for (int dt = 0; dt < 4; ++dt) {
;       const bf16_t* vp = Vt + (dt * 16 + r) * 264 + ks * 32 + quad * 4;
;       uint2 v0 = *(const uint2*)vp, v1 = *(const uint2*)(vp + 16);
;       bf16x8 av;
;       av[0] = (short)(v0.x & 0xffff); av[1] = (short)(v0.x >> 16); av[2] = (short)(v0.y & 0xffff); av[3] = (short)(v0.y >> 16);
;       av[4] = (short)(v1.x & 0xffff); av[5] = (short)(v1.x >> 16); av[6] = (short)(v1.y & 0xffff); av[7] = (short)(v1.y >> 16);
;       o[dt] = __builtin_amdgcn_mfma_f32_16x16x32_bf16(av, pb, o[dt], 0, 0, 0);
;     }
;   }
;   for (int dt = 0; dt < 4; ++dt) {
;     uint2 ov;
;     ov.x = pack2(o[dt][0] * inv, o[dt][1] * inv);
;     ov.y = pack2(o[dt][2] * inv, o[dt][3] * inv);
;     if (!dry) *(uint2*)(qp + dt * 16 + quad * 4) = ov;
;   }
	v_bfi_b32 v70, s65, v70, v70
	v_mfma_f32_16x16x32_bf16 v[64:67], v[64:67], v[42:45], v[72:75]
	v_sub_f32_e32 v2, v3, v59
	v_exp_f32_e32 v76, v8
	s_waitcnt lgkmcnt(0)
	v_bfi_b32 v48, s65, v48, v48
	v_mfma_f32_16x16x32_bf16 v[42:45], v[68:71], v[42:45], v[50:53]
	v_mul_f32_e32 v2, 0x3e38aa3b, v2
	v_exp_f32_e32 v28, v2
	ds_read2_b64 v[50:53], v7 offset0:64 offset1:68
	v_mfma_f32_16x16x32_bf16 v[46:49], v[46:49], v[34:37], v[60:63]
	v_add_f32_e32 v8, v90, v94
	v_add_f32_e32 v8, v76, v8
	v_add_f32_e32 v2, v9, v8
	ds_read2_b64 v[60:63], v20 offset0:128 offset1:132
	v_mfma_f32_16x16x32_bf16 v[30:33], v[30:33], v[34:37], v[38:41]
	s_waitcnt lgkmcnt(1)
	v_bfi_b32 v52, s65, v52, v52
	v_add_f32_e32 v8, v28, v2
	v_sub_f32_e32 v2, v4, v59
	ds_read2_b64 v[38:41], v21 offset0:40 offset1:44
	s_waitcnt lgkmcnt(1)
	v_bfi_b32 v62, s65, v62, v62
	v_mfma_f32_16x16x32_bf16 v[50:53], v[50:53], v[34:37], v[64:67]
	v_mul_f32_e32 v2, 0x3e38aa3b, v2
	s_waitcnt lgkmcnt(0)
	v_bfi_b32 v40, s65, v40, v40
	v_mfma_f32_16x16x32_bf16 v[34:37], v[60:63], v[34:37], v[42:45]
	ds_read2_b64 v[60:63], v0 offset0:104 offset1:108
	v_cvt_pk_bf16_f32 v26, v18, v19
	v_cvt_pk_bf16_f32 v25, v24, v25
	v_cvt_pk_bf16_f32 v24, v22, v23
	v_exp_f32_e32 v18, v2
	v_sub_f32_e32 v19, v5, v59
	ds_read2_b64 v[2:5], v21 offset0:48 offset1:52
	ds_read2_b64 v[42:45], v7 offset0:72 offset1:76
	v_mfma_f32_16x16x32_bf16 v[38:41], v[38:41], v[24:27], v[46:49]
	v_cvt_pk_bf16_f32 v13, v12, v13
	v_cvt_pk_bf16_f32 v12, v10, v11
	v_cvt_pk_bf16_f32 v11, v16, v17
	ds_read2_b64 v[46:49], v20 offset0:136 offset1:140
	v_cvt_pk_bf16_f32 v10, v14, v15
	ds_read2_b64 v[14:17], v0 offset0:112 offset1:116
	s_waitcnt lgkmcnt(4)
	v_bfi_b32 v62, s65, v62, v62
	s_waitcnt lgkmcnt(3)
	v_bfi_b32 v4, s65, v4, v4
	s_waitcnt lgkmcnt(2)
	v_bfi_b32 v44, s65, v44, v44
	s_waitcnt lgkmcnt(1)
	v_bfi_b32 v48, s65, v48, v48
	s_waitcnt lgkmcnt(0)
	v_bfi_b32 v16, s65, v16, v16
	v_mfma_f32_16x16x32_bf16 v[30:33], v[60:63], v[24:27], v[30:33]
	v_mul_f32_e32 v19, 0x3e38aa3b, v19
	v_exp_f32_e32 v19, v19
	v_mfma_f32_16x16x32_bf16 v[2:5], v[2:5], v[10:13], v[38:41]
	v_add_f32_e32 v8, v18, v8
	s_nop 1
	ds_read2_b64 v[38:41], v20 offset0:144 offset1:148
	v_mfma_f32_16x16x32_bf16 v[42:45], v[42:45], v[24:27], v[50:53]
	s_waitcnt lgkmcnt(0)
	v_bfi_b32 v40, s65, v40, v40
	v_mfma_f32_16x16x32_bf16 v[22:25], v[46:49], v[24:27], v[34:37]
	s_nop 2
	ds_read2_b64 v[34:37], v7 offset0:80 offset1:84
	v_mfma_f32_16x16x32_bf16 v[14:17], v[14:17], v[10:13], v[30:33]
	s_waitcnt lgkmcnt(0)
	v_bfi_b32 v36, s65, v36, v36
	s_nop 0
	ds_read2_b64 v[30:33], v21 offset0:56 offset1:60
	v_mfma_f32_16x16x32_bf16 v[22:25], v[38:41], v[10:13], v[22:25]
	v_cvt_pk_bf16_f32 v41, v18, v19
	v_cvt_pk_bf16_f32 v40, v9, v28
	v_cvt_pk_bf16_f32 v39, v90, v76
	s_waitcnt lgkmcnt(0)
	v_bfi_b32 v32, s65, v32, v32
	v_cvt_pk_bf16_f32 v38, v6, v29
	v_mfma_f32_16x16x32_bf16 v[34:37], v[34:37], v[10:13], v[42:45]
	v_add_f32_e32 v21, v19, v8
	ds_read2_b64 v[8:11], v7 offset0:88 offset1:92
	ds_read2_b64 v[26:29], v0 offset0:120 offset1:124
	v_mfma_f32_16x16x32_bf16 v[2:5], v[30:33], v[38:41], v[2:5]
	ds_read2_b64 v[30:33], v20 offset0:152 offset1:156
	ds_bpermute_b32 v0, v58, v21
	s_waitcnt lgkmcnt(3)
	v_bfi_b32 v10, s65, v10, v10
	s_waitcnt lgkmcnt(2)
	v_bfi_b32 v28, s65, v28, v28
	s_waitcnt lgkmcnt(1)
	v_bfi_b32 v32, s65, v32, v32
	s_waitcnt lgkmcnt(0)
	v_add_f32_e32 v0, v21, v0
	ds_bpermute_b32 v18, v57, v0
	v_mfma_f32_16x16x32_bf16 v[6:9], v[8:11], v[38:41], v[34:37]
	v_mfma_f32_16x16x32_bf16 v[10:13], v[26:29], v[38:41], v[14:17]
	v_mfma_f32_16x16x32_bf16 v[14:17], v[30:33], v[38:41], v[22:25]
	s_cbranch_vccnz .LBB0_1351
	s_waitcnt lgkmcnt(0)
	v_add_f32_e32 v0, v0, v18
	v_div_scale_f32 v18, s[4:5], v0, v0, 1.0
	v_rcp_f32_e32 v19, v18
	v_mov_b32_e32 v57, v1
	v_lshl_add_u64 v[20:21], v[54:55], 0, v[56:57]
	v_fma_f32 v22, -v18, v19, 1.0
	v_fmac_f32_e32 v19, v22, v19
	v_div_scale_f32 v22, vcc, 1.0, v0, 1.0
	v_mul_f32_e32 v23, v22, v19
	v_fma_f32 v24, -v18, v23, v22
	v_fmac_f32_e32 v23, v24, v19
	v_fma_f32 v18, -v18, v23, v22
	v_div_fmas_f32 v18, v18, v19, v23
	v_div_fixup_f32 v0, v18, v0, 1.0
	v_pk_mul_f32 v[4:5], v[0:1], v[4:5] op_sel_hi:[0,1]
	v_pk_mul_f32 v[2:3], v[0:1], v[2:3] op_sel_hi:[0,1]
	v_cvt_pk_bf16_f32 v5, v4, v5
	v_cvt_pk_bf16_f32 v4, v2, v3
	global_store_dwordx2 v[20:21], v[4:5], off
	v_pk_mul_f32 v[2:3], v[0:1], v[8:9] op_sel_hi:[0,1]
	v_pk_mul_f32 v[4:5], v[0:1], v[6:7] op_sel_hi:[0,1]
	v_cvt_pk_bf16_f32 v3, v2, v3
	v_cvt_pk_bf16_f32 v2, v4, v5
	global_store_dwordx2 v[20:21], v[2:3], off offset:32
	v_pk_mul_f32 v[2:3], v[0:1], v[12:13] op_sel_hi:[0,1]
	v_pk_mul_f32 v[4:5], v[0:1], v[10:11] op_sel_hi:[0,1]
	v_cvt_pk_bf16_f32 v3, v2, v3
	v_cvt_pk_bf16_f32 v2, v4, v5
	global_store_dwordx2 v[20:21], v[2:3], off offset:64
	v_pk_mul_f32 v[2:3], v[0:1], v[16:17] op_sel_hi:[0,1]
	v_pk_mul_f32 v[4:5], v[0:1], v[14:15] op_sel_hi:[0,1]
	v_cvt_pk_bf16_f32 v3, v2, v3
	v_cvt_pk_bf16_f32 v2, v4, v5
	global_store_dwordx2 v[20:21], v[2:3], off offset:96
